# v34: v31 + byte-phase alignment: K-loop heads 64-byte aligned, every 32-MFMA run starts on an 8-byte boundary
# speedup vs baseline: 1.0048x; 1.0014x over previous
.LBB0_229:
	s_ashr_i32 s57, s56, 31
	s_lshl_b64 s[30:31], s[56:57], 21
	s_add_u32 s24, s36, s30
	v_readlane_b32 s20, v254, 7
	s_addc_u32 s25, s20, s31
	s_and_b64 s[30:31], s[88:89], exec
	s_cselect_b32 s34, s25, s1
	s_cselect_b32 s35, s24, s0
	s_ashr_i32 s27, s26, 31
	s_lshl_b64 s[30:31], s[26:27], 21
	v_readlane_b32 s20, v254, 2
	s_add_u32 s20, s20, s30
	v_readlane_b32 s21, v254, 3
	s_addc_u32 s21, s21, s31
	s_and_b64 s[30:31], s[88:89], exec
	s_cselect_b32 s27, s21, s29
	s_cselect_b32 s40, s20, s28
	s_add_u32 s0, s0, 0x100080
	s_addc_u32 s1, s1, 0
	s_add_u32 s41, s28, 0x100
	v_mov_b64_e32 v[2:3], 0
	v_mov_b64_e32 v[4:5], 0
	v_mov_b64_e32 v[6:7], 0
	v_mov_b64_e32 v[8:9], 0
	v_mov_b64_e32 v[10:11], 0
	v_mov_b64_e32 v[12:13], 0
	v_mov_b64_e32 v[14:15], 0
	v_mov_b64_e32 v[16:17], 0
	v_mov_b64_e32 v[18:19], 0
	v_mov_b64_e32 v[20:21], 0
	v_mov_b64_e32 v[22:23], 0
	v_mov_b64_e32 v[24:25], 0
	v_mov_b64_e32 v[26:27], 0
	v_mov_b64_e32 v[28:29], 0
	v_mov_b64_e32 v[30:31], 0
	v_mov_b64_e32 v[32:33], 0
	v_mov_b64_e32 v[34:35], 0
	v_mov_b64_e32 v[36:37], 0
	v_mov_b64_e32 v[38:39], 0
	v_mov_b64_e32 v[40:41], 0
	v_mov_b64_e32 v[42:43], 0
	v_mov_b64_e32 v[44:45], 0
	v_mov_b64_e32 v[46:47], 0
	v_mov_b64_e32 v[48:49], 0
	v_mov_b64_e32 v[50:51], 0
	v_mov_b64_e32 v[52:53], 0
	v_mov_b64_e32 v[54:55], 0
	v_mov_b64_e32 v[56:57], 0
	v_mov_b64_e32 v[58:59], 0
	v_mov_b64_e32 v[60:61], 0
	v_mov_b64_e32 v[62:63], 0
	v_mov_b64_e32 v[64:65], 0
	v_mov_b64_e32 v[66:67], 0
	v_mov_b64_e32 v[68:69], 0
	v_mov_b64_e32 v[70:71], 0
	v_mov_b64_e32 v[72:73], 0
	v_mov_b64_e32 v[74:75], 0
	v_mov_b64_e32 v[76:77], 0
	v_mov_b64_e32 v[78:79], 0
	v_mov_b64_e32 v[80:81], 0
	v_mov_b64_e32 v[82:83], 0
	v_mov_b64_e32 v[84:85], 0
	v_mov_b64_e32 v[86:87], 0
	v_mov_b64_e32 v[88:89], 0
	v_mov_b64_e32 v[90:91], 0
	v_mov_b64_e32 v[92:93], 0
	v_mov_b64_e32 v[94:95], 0
	v_mov_b64_e32 v[96:97], 0
	v_mov_b64_e32 v[98:99], 0
	v_mov_b64_e32 v[100:101], 0
	v_mov_b64_e32 v[102:103], 0
	v_mov_b64_e32 v[104:105], 0
	v_mov_b64_e32 v[106:107], 0
	v_mov_b64_e32 v[108:109], 0
	v_mov_b64_e32 v[110:111], 0
	v_mov_b64_e32 v[112:113], 0
	v_mov_b64_e32 v[114:115], 0
	v_mov_b64_e32 v[116:117], 0
	v_mov_b64_e32 v[118:119], 0
	v_mov_b64_e32 v[120:121], 0
	v_mov_b64_e32 v[122:123], 0
	v_mov_b64_e32 v[124:125], 0
	v_mov_b64_e32 v[126:127], 0
	v_mov_b64_e32 v[128:129], 0
	s_addc_u32 s43, s29, 0
	s_mov_b32 s50, -2
	.p2align 6
.LBB0_230:
	s_add_u32 s98, s0, 0xfff00000
	s_addc_u32 s99, s1, -1
	s_add_u32 s28, s0, 0xfff00080
	s_addc_u32 s29, s1, -1
	s_add_i32 s51, 0, 0x10000
	s_cmp_eq_u32 s50, 60
	s_cselect_b32 s31, s34, s29
	s_cselect_b32 s30, s35, s28
	v_add_u32_e32 v0, s51, v179
	s_cselect_b32 s29, s27, s43
	s_cselect_b32 s28, s40, s41
	s_add_i32 s77, 0, 0x14000
	ds_read_b128 v[130:133], v0
	ds_read_b128 v[134:137], v0 offset:1024
	ds_read_b128 v[138:141], v0 offset:2048
	ds_read_b128 v[142:145], v0 offset:3072
	v_add_u32_e32 v0, s77, v179
	ds_read_b128 v[146:149], v0
	ds_read_b128 v[150:153], v0 offset:1024
	ds_read_b128 v[154:157], v0 offset:2048
	ds_read_b128 v[158:161], v0 offset:3072
	s_mov_b32 m0, s54
	ds_read_b128 v[174:177], v192
	ds_read_b128 v[180:183], v192 offset:1024
	ds_read_b128 v[184:187], v192 offset:2048
	ds_read_b128 v[188:191], v192 offset:3072
	ds_read_b128 v[200:203], v192 offset:4096
	ds_read_b128 v[204:207], v192 offset:5120
	ds_read_b128 v[208:211], v192 offset:6144
	ds_read_b128 v[212:215], v192 offset:7168
	global_load_lds_dwordx4 v168, s[98:99]
	s_mov_b32 m0, s55
	s_nop 0
	global_load_lds_dwordx4 v164, s[98:99]
	s_add_i32 m0, s14, 0xc000
	s_nop 0
	global_load_lds_dwordx4 v170, s[0:1]
	s_add_i32 m0, s14, 0xe000
	s_nop 0
	global_load_lds_dwordx4 v172, s[0:1]
	s_waitcnt vmcnt(8)
	s_waitcnt lgkmcnt(0)
	s_barrier
	s_waitcnt lgkmcnt(0)
	v_mfma_f32_16x16x32_bf16 v[126:129], v[130:133], v[174:177], v[126:129]
	v_mfma_f32_16x16x32_bf16 v[126:129], v[134:137], v[180:183], v[126:129]
	v_mfma_f32_16x16x32_bf16 v[110:113], v[130:133], v[184:187], v[110:113]
	v_mfma_f32_16x16x32_bf16 v[110:113], v[134:137], v[188:191], v[110:113]
	v_mfma_f32_16x16x32_bf16 v[94:97], v[130:133], v[200:203], v[94:97]
	v_mfma_f32_16x16x32_bf16 v[94:97], v[134:137], v[204:207], v[94:97]
	v_mfma_f32_16x16x32_bf16 v[78:81], v[130:133], v[208:211], v[78:81]
	v_mfma_f32_16x16x32_bf16 v[78:81], v[134:137], v[212:215], v[78:81]
	v_mfma_f32_16x16x32_bf16 v[122:125], v[138:141], v[174:177], v[122:125]
	v_mfma_f32_16x16x32_bf16 v[122:125], v[142:145], v[180:183], v[122:125]
	v_mfma_f32_16x16x32_bf16 v[106:109], v[138:141], v[184:187], v[106:109]
	v_mfma_f32_16x16x32_bf16 v[106:109], v[142:145], v[188:191], v[106:109]
	v_mfma_f32_16x16x32_bf16 v[90:93], v[138:141], v[200:203], v[90:93]
	v_mfma_f32_16x16x32_bf16 v[90:93], v[142:145], v[204:207], v[90:93]
	v_mfma_f32_16x16x32_bf16 v[74:77], v[138:141], v[208:211], v[74:77]
	v_mfma_f32_16x16x32_bf16 v[74:77], v[142:145], v[212:215], v[74:77]
	v_mfma_f32_16x16x32_bf16 v[118:121], v[146:149], v[174:177], v[118:121]
	v_mfma_f32_16x16x32_bf16 v[118:121], v[150:153], v[180:183], v[118:121]
	v_mfma_f32_16x16x32_bf16 v[102:105], v[146:149], v[184:187], v[102:105]
	v_mfma_f32_16x16x32_bf16 v[102:105], v[150:153], v[188:191], v[102:105]
	v_mfma_f32_16x16x32_bf16 v[86:89], v[146:149], v[200:203], v[86:89]
	v_mfma_f32_16x16x32_bf16 v[86:89], v[150:153], v[204:207], v[86:89]
	v_mfma_f32_16x16x32_bf16 v[70:73], v[146:149], v[208:211], v[70:73]
	v_mfma_f32_16x16x32_bf16 v[70:73], v[150:153], v[212:215], v[70:73]
	v_mfma_f32_16x16x32_bf16 v[114:117], v[154:157], v[174:177], v[114:117]
	v_mfma_f32_16x16x32_bf16 v[114:117], v[158:161], v[180:183], v[114:117]
	v_mfma_f32_16x16x32_bf16 v[98:101], v[154:157], v[184:187], v[98:101]
	v_mfma_f32_16x16x32_bf16 v[98:101], v[158:161], v[188:191], v[98:101]
	v_mfma_f32_16x16x32_bf16 v[82:85], v[154:157], v[200:203], v[82:85]
	v_mfma_f32_16x16x32_bf16 v[82:85], v[158:161], v[204:207], v[82:85]
	v_mfma_f32_16x16x32_bf16 v[66:69], v[154:157], v[208:211], v[66:69]
	v_mfma_f32_16x16x32_bf16 v[66:69], v[158:161], v[212:215], v[66:69]
	s_barrier
	s_add_i32 s51, s51, s9
	s_mov_b32 m0, s51
	ds_read_b128 v[174:177], v192 offset:16384
	ds_read_b128 v[180:183], v192 offset:17408
	ds_read_b128 v[184:187], v192 offset:18432
	ds_read_b128 v[188:191], v192 offset:19456
	ds_read_b128 v[200:203], v192 offset:20480
	ds_read_b128 v[204:207], v192 offset:21504
	ds_read_b128 v[208:211], v192 offset:22528
	ds_read_b128 v[212:215], v192 offset:23552
	global_load_lds_dwordx4 v166, s[28:29]
	s_add_i32 m0, s51, 0x2000
	s_add_u32 s80, s28, 0x100000
	s_addc_u32 s81, s29, 0
	s_add_i32 s51, s77, s9
	global_load_lds_dwordx4 v162, s[28:29]
	s_mov_b32 m0, s51
	s_nop 0
	global_load_lds_dwordx4 v166, s[80:81]
	s_add_i32 m0, s51, 0x2000
	s_nop 0
	global_load_lds_dwordx4 v162, s[80:81]
	s_waitcnt vmcnt(6)
	s_waitcnt lgkmcnt(0)
	s_barrier
	s_waitcnt lgkmcnt(0)
	v_mfma_f32_16x16x32_bf16 v[62:65], v[130:133], v[174:177], v[62:65]
	v_mfma_f32_16x16x32_bf16 v[62:65], v[134:137], v[180:183], v[62:65]
	v_mfma_f32_16x16x32_bf16 v[46:49], v[130:133], v[184:187], v[46:49]
	v_mfma_f32_16x16x32_bf16 v[46:49], v[134:137], v[188:191], v[46:49]
	v_mfma_f32_16x16x32_bf16 v[30:33], v[130:133], v[200:203], v[30:33]
	v_mfma_f32_16x16x32_bf16 v[30:33], v[134:137], v[204:207], v[30:33]
	v_mfma_f32_16x16x32_bf16 v[14:17], v[130:133], v[208:211], v[14:17]
	v_mfma_f32_16x16x32_bf16 v[14:17], v[134:137], v[212:215], v[14:17]
	v_mfma_f32_16x16x32_bf16 v[58:61], v[138:141], v[174:177], v[58:61]
	v_mfma_f32_16x16x32_bf16 v[58:61], v[142:145], v[180:183], v[58:61]
	v_mfma_f32_16x16x32_bf16 v[42:45], v[138:141], v[184:187], v[42:45]
	v_mfma_f32_16x16x32_bf16 v[42:45], v[142:145], v[188:191], v[42:45]
	v_mfma_f32_16x16x32_bf16 v[26:29], v[138:141], v[200:203], v[26:29]
	v_mfma_f32_16x16x32_bf16 v[26:29], v[142:145], v[204:207], v[26:29]
	v_mfma_f32_16x16x32_bf16 v[10:13], v[138:141], v[208:211], v[10:13]
	v_mfma_f32_16x16x32_bf16 v[10:13], v[142:145], v[212:215], v[10:13]
	v_mfma_f32_16x16x32_bf16 v[54:57], v[146:149], v[174:177], v[54:57]
	v_mfma_f32_16x16x32_bf16 v[54:57], v[150:153], v[180:183], v[54:57]
	v_mfma_f32_16x16x32_bf16 v[38:41], v[146:149], v[184:187], v[38:41]
	v_mfma_f32_16x16x32_bf16 v[38:41], v[150:153], v[188:191], v[38:41]
	v_mfma_f32_16x16x32_bf16 v[22:25], v[146:149], v[200:203], v[22:25]
	v_mfma_f32_16x16x32_bf16 v[22:25], v[150:153], v[204:207], v[22:25]
	v_mfma_f32_16x16x32_bf16 v[6:9], v[146:149], v[208:211], v[6:9]
	v_mfma_f32_16x16x32_bf16 v[6:9], v[150:153], v[212:215], v[6:9]
	v_mfma_f32_16x16x32_bf16 v[50:53], v[154:157], v[174:177], v[50:53]
	v_mfma_f32_16x16x32_bf16 v[50:53], v[158:161], v[180:183], v[50:53]
	v_mfma_f32_16x16x32_bf16 v[34:37], v[154:157], v[184:187], v[34:37]
	v_mfma_f32_16x16x32_bf16 v[34:37], v[158:161], v[188:191], v[34:37]
	v_mfma_f32_16x16x32_bf16 v[18:21], v[154:157], v[200:203], v[18:21]
	v_mfma_f32_16x16x32_bf16 v[18:21], v[158:161], v[204:207], v[18:21]
	v_mfma_f32_16x16x32_bf16 v[2:5], v[154:157], v[208:211], v[2:5]
	v_mfma_f32_16x16x32_bf16 v[2:5], v[158:161], v[212:215], v[2:5]
	s_barrier
	s_nop 0
	s_add_i32 s51, 0, 0x18000
	v_add_u32_e32 v0, s51, v179
	s_add_i32 s77, 0, 0x1c000
	ds_read_b128 v[130:133], v0
	ds_read_b128 v[134:137], v0 offset:1024
	ds_read_b128 v[138:141], v0 offset:2048
	ds_read_b128 v[142:145], v0 offset:3072
	v_add_u32_e32 v0, s77, v179
	ds_read_b128 v[146:149], v0
	ds_read_b128 v[150:153], v0 offset:1024
	ds_read_b128 v[154:157], v0 offset:2048
	ds_read_b128 v[158:161], v0 offset:3072
	s_mov_b32 m0, s14
	ds_read_b128 v[174:177], v192 offset:32768
	ds_read_b128 v[180:183], v192 offset:33792
	ds_read_b128 v[184:187], v192 offset:34816
	ds_read_b128 v[188:191], v192 offset:35840
	ds_read_b128 v[200:203], v192 offset:36864
	ds_read_b128 v[204:207], v192 offset:37888
	ds_read_b128 v[208:211], v192 offset:38912
	ds_read_b128 v[212:215], v192 offset:39936
	global_load_lds_dwordx4 v168, s[30:31]
	s_mov_b32 m0, s15
	s_nop 0
	global_load_lds_dwordx4 v164, s[30:31]
	s_add_u32 s30, s30, 0x100000
	s_addc_u32 s31, s31, 0
	s_mov_b32 m0, s52
	s_nop 0
	global_load_lds_dwordx4 v168, s[30:31]
	s_mov_b32 m0, s53
	s_nop 0
	global_load_lds_dwordx4 v164, s[30:31]
	s_waitcnt vmcnt(8)
	s_waitcnt lgkmcnt(0)
	s_barrier
	s_waitcnt lgkmcnt(0)
	v_mfma_f32_16x16x32_bf16 v[126:129], v[130:133], v[174:177], v[126:129]
	v_mfma_f32_16x16x32_bf16 v[126:129], v[134:137], v[180:183], v[126:129]
	v_mfma_f32_16x16x32_bf16 v[110:113], v[130:133], v[184:187], v[110:113]
	v_mfma_f32_16x16x32_bf16 v[110:113], v[134:137], v[188:191], v[110:113]
	v_mfma_f32_16x16x32_bf16 v[94:97], v[130:133], v[200:203], v[94:97]
	v_mfma_f32_16x16x32_bf16 v[94:97], v[134:137], v[204:207], v[94:97]
	v_mfma_f32_16x16x32_bf16 v[78:81], v[130:133], v[208:211], v[78:81]
	v_mfma_f32_16x16x32_bf16 v[78:81], v[134:137], v[212:215], v[78:81]
	v_mfma_f32_16x16x32_bf16 v[122:125], v[138:141], v[174:177], v[122:125]
	v_mfma_f32_16x16x32_bf16 v[122:125], v[142:145], v[180:183], v[122:125]
	v_mfma_f32_16x16x32_bf16 v[106:109], v[138:141], v[184:187], v[106:109]
	v_mfma_f32_16x16x32_bf16 v[106:109], v[142:145], v[188:191], v[106:109]
	v_mfma_f32_16x16x32_bf16 v[90:93], v[138:141], v[200:203], v[90:93]
	v_mfma_f32_16x16x32_bf16 v[90:93], v[142:145], v[204:207], v[90:93]
	v_mfma_f32_16x16x32_bf16 v[74:77], v[138:141], v[208:211], v[74:77]
	v_mfma_f32_16x16x32_bf16 v[74:77], v[142:145], v[212:215], v[74:77]
	v_mfma_f32_16x16x32_bf16 v[118:121], v[146:149], v[174:177], v[118:121]
	v_mfma_f32_16x16x32_bf16 v[118:121], v[150:153], v[180:183], v[118:121]
	v_mfma_f32_16x16x32_bf16 v[102:105], v[146:149], v[184:187], v[102:105]
	v_mfma_f32_16x16x32_bf16 v[102:105], v[150:153], v[188:191], v[102:105]
	v_mfma_f32_16x16x32_bf16 v[86:89], v[146:149], v[200:203], v[86:89]
	v_mfma_f32_16x16x32_bf16 v[86:89], v[150:153], v[204:207], v[86:89]
	v_mfma_f32_16x16x32_bf16 v[70:73], v[146:149], v[208:211], v[70:73]
	v_mfma_f32_16x16x32_bf16 v[70:73], v[150:153], v[212:215], v[70:73]
	v_mfma_f32_16x16x32_bf16 v[114:117], v[154:157], v[174:177], v[114:117]
	v_mfma_f32_16x16x32_bf16 v[114:117], v[158:161], v[180:183], v[114:117]
	v_mfma_f32_16x16x32_bf16 v[98:101], v[154:157], v[184:187], v[98:101]
	v_mfma_f32_16x16x32_bf16 v[98:101], v[158:161], v[188:191], v[98:101]
	v_mfma_f32_16x16x32_bf16 v[82:85], v[154:157], v[200:203], v[82:85]
	v_mfma_f32_16x16x32_bf16 v[82:85], v[158:161], v[204:207], v[82:85]
	v_mfma_f32_16x16x32_bf16 v[66:69], v[154:157], v[208:211], v[66:69]
	v_mfma_f32_16x16x32_bf16 v[66:69], v[158:161], v[212:215], v[66:69]
	s_barrier
	s_nop 0
	s_add_u32 s98, s28, 0x80
	s_addc_u32 s99, s29, 0
	s_add_i32 s30, s51, s9
	s_mov_b32 m0, s30
	ds_read_b128 v[174:177], v192 offset:49152
	ds_read_b128 v[180:183], v192 offset:50176
	ds_read_b128 v[184:187], v192 offset:51200
	ds_read_b128 v[188:191], v192 offset:52224
	ds_read_b128 v[200:203], v192 offset:53248
	ds_read_b128 v[204:207], v192 offset:54272
	ds_read_b128 v[208:211], v192 offset:55296
	ds_read_b128 v[212:215], v192 offset:56320
	global_load_lds_dwordx4 v166, s[98:99]
	s_add_i32 m0, s30, 0x2000
	s_add_u32 s28, s28, 0x100080
	s_addc_u32 s29, s29, 0
	s_add_i32 s30, s77, s9
	global_load_lds_dwordx4 v162, s[98:99]
	s_mov_b32 m0, s30
	s_nop 0
	global_load_lds_dwordx4 v166, s[28:29]
	s_add_i32 m0, s30, 0x2000
	s_nop 0
	global_load_lds_dwordx4 v162, s[28:29]
	s_waitcnt vmcnt(6)
	s_waitcnt lgkmcnt(0)
	s_barrier
	s_waitcnt lgkmcnt(0)
	v_mfma_f32_16x16x32_bf16 v[62:65], v[130:133], v[174:177], v[62:65]
	v_mfma_f32_16x16x32_bf16 v[62:65], v[134:137], v[180:183], v[62:65]
	v_mfma_f32_16x16x32_bf16 v[46:49], v[130:133], v[184:187], v[46:49]
	v_mfma_f32_16x16x32_bf16 v[46:49], v[134:137], v[188:191], v[46:49]
	v_mfma_f32_16x16x32_bf16 v[30:33], v[130:133], v[200:203], v[30:33]
	v_mfma_f32_16x16x32_bf16 v[30:33], v[134:137], v[204:207], v[30:33]
	v_mfma_f32_16x16x32_bf16 v[14:17], v[130:133], v[208:211], v[14:17]
	v_mfma_f32_16x16x32_bf16 v[14:17], v[134:137], v[212:215], v[14:17]
	v_mfma_f32_16x16x32_bf16 v[58:61], v[138:141], v[174:177], v[58:61]
	v_mfma_f32_16x16x32_bf16 v[58:61], v[142:145], v[180:183], v[58:61]
	v_mfma_f32_16x16x32_bf16 v[42:45], v[138:141], v[184:187], v[42:45]
	v_mfma_f32_16x16x32_bf16 v[42:45], v[142:145], v[188:191], v[42:45]
	v_mfma_f32_16x16x32_bf16 v[26:29], v[138:141], v[200:203], v[26:29]
	v_mfma_f32_16x16x32_bf16 v[26:29], v[142:145], v[204:207], v[26:29]
	v_mfma_f32_16x16x32_bf16 v[10:13], v[138:141], v[208:211], v[10:13]
	v_mfma_f32_16x16x32_bf16 v[10:13], v[142:145], v[212:215], v[10:13]
	v_mfma_f32_16x16x32_bf16 v[54:57], v[146:149], v[174:177], v[54:57]
	v_mfma_f32_16x16x32_bf16 v[54:57], v[150:153], v[180:183], v[54:57]
	v_mfma_f32_16x16x32_bf16 v[38:41], v[146:149], v[184:187], v[38:41]
	v_mfma_f32_16x16x32_bf16 v[38:41], v[150:153], v[188:191], v[38:41]
	v_mfma_f32_16x16x32_bf16 v[22:25], v[146:149], v[200:203], v[22:25]
	v_mfma_f32_16x16x32_bf16 v[22:25], v[150:153], v[204:207], v[22:25]
	v_mfma_f32_16x16x32_bf16 v[6:9], v[146:149], v[208:211], v[6:9]
	v_mfma_f32_16x16x32_bf16 v[6:9], v[150:153], v[212:215], v[6:9]
	v_mfma_f32_16x16x32_bf16 v[50:53], v[154:157], v[174:177], v[50:53]
	v_mfma_f32_16x16x32_bf16 v[50:53], v[158:161], v[180:183], v[50:53]
	v_mfma_f32_16x16x32_bf16 v[34:37], v[154:157], v[184:187], v[34:37]
	v_mfma_f32_16x16x32_bf16 v[34:37], v[158:161], v[188:191], v[34:37]
	v_mfma_f32_16x16x32_bf16 v[18:21], v[154:157], v[200:203], v[18:21]
	v_mfma_f32_16x16x32_bf16 v[18:21], v[158:161], v[204:207], v[18:21]
	v_mfma_f32_16x16x32_bf16 v[2:5], v[154:157], v[208:211], v[2:5]
	v_mfma_f32_16x16x32_bf16 v[2:5], v[158:161], v[212:215], v[2:5]
	s_barrier
	s_add_i32 s50, s50, 2
	s_add_u32 s0, s0, 0x100
	s_addc_u32 s1, s1, 0
	s_add_u32 s41, s41, 0x100
	s_addc_u32 s43, s43, 0
	s_cmp_gt_u32 s50, 61
	s_cbranch_scc0 .LBB0_230
	s_and_b64 vcc, exec, s[22:23]
	s_cbranch_vccz .LBB0_233
	s_barrier

.LBB0_299:
	s_ashr_i32 s49, s48, 31
	s_lshl_b64 s[18:19], s[48:49], 20
	s_add_u32 s22, s92, s18
	v_readlane_b32 s18, v251, 32
	s_addc_u32 s23, s18, s19
	s_and_b64 s[18:19], s[38:39], exec
	s_cselect_b32 s18, s23, s1
	s_cselect_b32 s19, s22, s0
	s_ashr_i32 s27, s26, 31
	s_lshl_b64 s[24:25], s[26:27], 20
	s_add_u32 s24, s80, s24
	s_addc_u32 s25, s33, s25
	s_and_b64 s[30:31], s[38:39], exec
	s_cselect_b32 s27, s25, s29
	s_cselect_b32 s34, s24, s28
	s_add_u32 s0, s0, 0x80080
	s_addc_u32 s1, s1, 0
	s_add_u32 s35, s28, 0x100
	v_mov_b64_e32 v[18:19], 0
	v_mov_b64_e32 v[20:21], 0
	v_mov_b64_e32 v[22:23], 0
	v_mov_b64_e32 v[24:25], 0
	v_mov_b64_e32 v[26:27], 0
	v_mov_b64_e32 v[28:29], 0
	v_mov_b64_e32 v[30:31], 0
	v_mov_b64_e32 v[32:33], 0
	v_mov_b64_e32 v[34:35], 0
	v_mov_b64_e32 v[36:37], 0
	v_mov_b64_e32 v[38:39], 0
	v_mov_b64_e32 v[40:41], 0
	v_mov_b64_e32 v[42:43], 0
	v_mov_b64_e32 v[44:45], 0
	v_mov_b64_e32 v[46:47], 0
	v_mov_b64_e32 v[48:49], 0
	v_mov_b64_e32 v[50:51], 0
	v_mov_b64_e32 v[52:53], 0
	v_mov_b64_e32 v[54:55], 0
	v_mov_b64_e32 v[56:57], 0
	v_mov_b64_e32 v[58:59], 0
	v_mov_b64_e32 v[60:61], 0
	v_mov_b64_e32 v[62:63], 0
	v_mov_b64_e32 v[64:65], 0
	v_mov_b64_e32 v[66:67], 0
	v_mov_b64_e32 v[68:69], 0
	v_mov_b64_e32 v[70:71], 0
	v_mov_b64_e32 v[72:73], 0
	v_mov_b64_e32 v[74:75], 0
	v_mov_b64_e32 v[76:77], 0
	v_mov_b64_e32 v[78:79], 0
	v_mov_b64_e32 v[80:81], 0
	v_mov_b64_e32 v[82:83], 0
	v_mov_b64_e32 v[84:85], 0
	v_mov_b64_e32 v[86:87], 0
	v_mov_b64_e32 v[88:89], 0
	v_mov_b64_e32 v[90:91], 0
	v_mov_b64_e32 v[92:93], 0
	v_mov_b64_e32 v[94:95], 0
	v_mov_b64_e32 v[96:97], 0
	v_mov_b64_e32 v[98:99], 0
	v_mov_b64_e32 v[100:101], 0
	v_mov_b64_e32 v[102:103], 0
	v_mov_b64_e32 v[104:105], 0
	v_mov_b64_e32 v[106:107], 0
	v_mov_b64_e32 v[108:109], 0
	v_mov_b64_e32 v[110:111], 0
	v_mov_b64_e32 v[112:113], 0
	v_mov_b64_e32 v[114:115], 0
	v_mov_b64_e32 v[116:117], 0
	v_mov_b64_e32 v[118:119], 0
	v_mov_b64_e32 v[120:121], 0
	v_mov_b64_e32 v[122:123], 0
	v_mov_b64_e32 v[124:125], 0
	v_mov_b64_e32 v[126:127], 0
	v_mov_b64_e32 v[128:129], 0
	v_mov_b64_e32 v[130:131], 0
	v_mov_b64_e32 v[132:133], 0
	v_mov_b64_e32 v[134:135], 0
	v_mov_b64_e32 v[136:137], 0
	v_mov_b64_e32 v[138:139], 0
	v_mov_b64_e32 v[140:141], 0
	v_mov_b64_e32 v[142:143], 0
	v_mov_b64_e32 v[144:145], 0
	s_addc_u32 s40, s29, 0
	s_mov_b32 s41, -2
	.p2align 6

.Lspf_j1:
	s_waitcnt lgkmcnt(0)
	s_barrier
	s_waitcnt lgkmcnt(0)
	v_mfma_i32_16x16x64_i8 v[78:81], v[2:5], v[174:177], v[78:81]
	v_mfma_i32_16x16x64_i8 v[78:81], v[6:9], v[178:181], v[78:81]
	v_mfma_i32_16x16x64_i8 v[74:77], v[10:13], v[174:177], v[74:77]
	v_mfma_i32_16x16x64_i8 v[74:77], v[14:17], v[178:181], v[74:77]
	v_mfma_i32_16x16x64_i8 v[70:73], v[2:5], v[182:185], v[70:73]
	v_mfma_i32_16x16x64_i8 v[70:73], v[6:9], v[186:189], v[70:73]
	v_mfma_i32_16x16x64_i8 v[66:69], v[10:13], v[182:185], v[66:69]
	v_mfma_i32_16x16x64_i8 v[66:69], v[14:17], v[186:189], v[66:69]
	v_mfma_i32_16x16x64_i8 v[54:57], v[2:5], v[190:193], v[54:57]
	v_mfma_i32_16x16x64_i8 v[54:57], v[6:9], v[200:203], v[54:57]
	v_mfma_i32_16x16x64_i8 v[50:53], v[10:13], v[190:193], v[50:53]
	v_mfma_i32_16x16x64_i8 v[50:53], v[14:17], v[200:203], v[50:53]
	v_mfma_i32_16x16x64_i8 v[2:5], v[2:5], v[204:207], v[38:41]
	v_mfma_i32_16x16x64_i8 v[2:5], v[6:9], v[208:211], v[2:5]
	v_mfma_i32_16x16x64_i8 v[6:9], v[10:13], v[204:207], v[34:37]
	v_mfma_i32_16x16x64_i8 v[6:9], v[14:17], v[208:211], v[6:9]
	v_mfma_i32_16x16x64_i8 v[34:37], v[146:149], v[182:185], v[46:49]
	v_mfma_i32_16x16x64_i8 v[46:49], v[150:153], v[186:189], v[34:37]
	v_mfma_i32_16x16x64_i8 v[34:37], v[154:157], v[182:185], v[42:45]
	v_mfma_i32_16x16x64_i8 v[42:45], v[158:161], v[186:189], v[34:37]
	v_mfma_i32_16x16x64_i8 v[30:33], v[146:149], v[190:193], v[30:33]
	v_mfma_i32_16x16x64_i8 v[30:33], v[150:153], v[200:203], v[30:33]
	v_mfma_i32_16x16x64_i8 v[26:29], v[154:157], v[190:193], v[26:29]
	v_mfma_i32_16x16x64_i8 v[26:29], v[158:161], v[200:203], v[26:29]
	v_mfma_i32_16x16x64_i8 v[22:25], v[146:149], v[204:207], v[22:25]
	v_mfma_i32_16x16x64_i8 v[22:25], v[150:153], v[208:211], v[22:25]
	v_mfma_i32_16x16x64_i8 v[18:21], v[154:157], v[204:207], v[18:21]
	v_mfma_i32_16x16x64_i8 v[18:21], v[158:161], v[208:211], v[18:21]
	v_mfma_i32_16x16x64_i8 v[10:13], v[146:149], v[174:177], v[62:65]
	v_mfma_i32_16x16x64_i8 v[10:13], v[150:153], v[178:181], v[10:13]
	v_mfma_i32_16x16x64_i8 v[14:17], v[154:157], v[174:177], v[58:61]
	v_mfma_i32_16x16x64_i8 v[14:17], v[158:161], v[178:181], v[14:17]
	s_barrier
	s_nop 0
	s_add_i32 s42, 0, 0x18000
	v_add_u32_e32 v0, s42, v199
	s_add_i32 s43, 0, 0x1c000
	ds_read_b128 v[34:37], v0
	ds_read_b128 v[38:41], v0 offset:1024
	ds_read_b128 v[58:61], v0 offset:2048
	ds_read_b128 v[62:65], v0 offset:3072
	v_add_u32_e32 v0, s43, v199
	ds_read_b128 v[146:149], v0
	ds_read_b128 v[150:153], v0 offset:1024
	ds_read_b128 v[154:157], v0 offset:2048
	ds_read_b128 v[158:161], v0 offset:3072
	s_mov_b32 m0, s21
	ds_read_b128 v[174:177], v250 offset:32768
	ds_read_b128 v[178:181], v250 offset:33792
	ds_read_b128 v[182:185], v250 offset:34816
	ds_read_b128 v[186:189], v250 offset:35840
	ds_read_b128 v[190:193], v250 offset:36864
	ds_read_b128 v[200:203], v250 offset:37888
	ds_read_b128 v[204:207], v250 offset:38912
	ds_read_b128 v[208:211], v250 offset:39936
	global_load_lds_dwordx4 v162, s[30:31]
	s_mov_b32 m0, s57
	s_nop 0
	global_load_lds_dwordx4 v166, s[30:31]
	s_add_u32 s30, s30, 0x80000
	s_addc_u32 s31, s31, 0
	s_mov_b32 m0, s73
	s_nop 0
	global_load_lds_dwordx4 v162, s[30:31]
	s_mov_b32 m0, s76
	s_nop 0
	global_load_lds_dwordx4 v166, s[30:31]
	s_cmp_eq_u32 s41, 28
	s_cbranch_scc1 .Lspf_w2
	s_waitcnt vmcnt(8)
	s_branch .Lspf_j2

.Lspf_j2:
	s_waitcnt lgkmcnt(0)
	s_barrier
	s_waitcnt lgkmcnt(0)
	v_mfma_i32_16x16x64_i8 v[142:145], v[34:37], v[174:177], v[142:145]
	v_mfma_i32_16x16x64_i8 v[142:145], v[38:41], v[178:181], v[142:145]
	v_mfma_i32_16x16x64_i8 v[134:137], v[34:37], v[182:185], v[134:137]
	v_mfma_i32_16x16x64_i8 v[134:137], v[38:41], v[186:189], v[134:137]
	v_mfma_i32_16x16x64_i8 v[122:125], v[34:37], v[190:193], v[122:125]
	v_mfma_i32_16x16x64_i8 v[122:125], v[38:41], v[200:203], v[122:125]
	v_mfma_i32_16x16x64_i8 v[106:109], v[34:37], v[204:207], v[106:109]
	v_mfma_i32_16x16x64_i8 v[106:109], v[38:41], v[208:211], v[106:109]
	v_mfma_i32_16x16x64_i8 v[138:141], v[58:61], v[174:177], v[138:141]
	v_mfma_i32_16x16x64_i8 v[138:141], v[62:65], v[178:181], v[138:141]
	v_mfma_i32_16x16x64_i8 v[130:133], v[58:61], v[182:185], v[130:133]
	v_mfma_i32_16x16x64_i8 v[130:133], v[62:65], v[186:189], v[130:133]
	v_mfma_i32_16x16x64_i8 v[114:117], v[58:61], v[190:193], v[114:117]
	v_mfma_i32_16x16x64_i8 v[114:117], v[62:65], v[200:203], v[114:117]
	v_mfma_i32_16x16x64_i8 v[98:101], v[58:61], v[204:207], v[98:101]
	v_mfma_i32_16x16x64_i8 v[98:101], v[62:65], v[208:211], v[98:101]
	v_mfma_i32_16x16x64_i8 v[126:129], v[146:149], v[174:177], v[126:129]
	v_mfma_i32_16x16x64_i8 v[126:129], v[150:153], v[178:181], v[126:129]
	v_mfma_i32_16x16x64_i8 v[110:113], v[146:149], v[182:185], v[110:113]
	v_mfma_i32_16x16x64_i8 v[110:113], v[150:153], v[186:189], v[110:113]
	v_mfma_i32_16x16x64_i8 v[94:97], v[146:149], v[190:193], v[94:97]
	v_mfma_i32_16x16x64_i8 v[94:97], v[150:153], v[200:203], v[94:97]
	v_mfma_i32_16x16x64_i8 v[86:89], v[146:149], v[204:207], v[86:89]
	v_mfma_i32_16x16x64_i8 v[86:89], v[150:153], v[208:211], v[86:89]
	v_mfma_i32_16x16x64_i8 v[118:121], v[154:157], v[174:177], v[118:121]
	v_mfma_i32_16x16x64_i8 v[118:121], v[158:161], v[178:181], v[118:121]
	v_mfma_i32_16x16x64_i8 v[102:105], v[154:157], v[182:185], v[102:105]
	v_mfma_i32_16x16x64_i8 v[102:105], v[158:161], v[186:189], v[102:105]
	v_mfma_i32_16x16x64_i8 v[90:93], v[154:157], v[190:193], v[90:93]
	v_mfma_i32_16x16x64_i8 v[90:93], v[158:161], v[200:203], v[90:93]
	v_mfma_i32_16x16x64_i8 v[82:85], v[154:157], v[204:207], v[82:85]
	v_mfma_i32_16x16x64_i8 v[82:85], v[158:161], v[208:211], v[82:85]
	s_barrier
	s_nop 0
	s_add_i32 s30, s42, s81
	s_add_u32 s98, s28, 0x80
	s_addc_u32 s99, s29, 0
	s_mov_b32 m0, s30
	ds_read_b128 v[174:177], v250 offset:49152
	ds_read_b128 v[178:181], v250 offset:50176
	ds_read_b128 v[182:185], v250 offset:51200
	ds_read_b128 v[186:189], v250 offset:52224
	ds_read_b128 v[190:193], v250 offset:53248
	ds_read_b128 v[200:203], v250 offset:54272
	ds_read_b128 v[204:207], v250 offset:55296
	ds_read_b128 v[208:211], v250 offset:56320
	global_load_lds_dwordx4 v164, s[98:99]
	s_add_i32 m0, s30, 0x2000
	s_add_u32 s28, s28, 0x80080
	s_addc_u32 s29, s29, 0
	s_add_i32 s30, s43, s81
	global_load_lds_dwordx4 v168, s[98:99]
	s_mov_b32 m0, s30
	s_nop 0
	global_load_lds_dwordx4 v164, s[28:29]
	s_add_i32 m0, s30, 0x2000
	s_nop 0
	global_load_lds_dwordx4 v168, s[28:29]
	s_waitcnt vmcnt(6)
	s_waitcnt lgkmcnt(0)
	s_barrier
	s_waitcnt lgkmcnt(0)
	v_mfma_i32_16x16x64_i8 v[78:81], v[34:37], v[174:177], v[78:81]
	v_mfma_i32_16x16x64_i8 v[78:81], v[38:41], v[178:181], v[78:81]
	v_mfma_i32_16x16x64_i8 v[70:73], v[34:37], v[182:185], v[70:73]
	v_mfma_i32_16x16x64_i8 v[70:73], v[38:41], v[186:189], v[70:73]
	v_mfma_i32_16x16x64_i8 v[54:57], v[34:37], v[190:193], v[54:57]
	v_mfma_i32_16x16x64_i8 v[54:57], v[38:41], v[200:203], v[54:57]
	v_mfma_i32_16x16x64_i8 v[2:5], v[34:37], v[204:207], v[2:5]
	v_mfma_i32_16x16x64_i8 v[38:41], v[38:41], v[208:211], v[2:5]
	v_mfma_i32_16x16x64_i8 v[74:77], v[58:61], v[174:177], v[74:77]
	v_mfma_i32_16x16x64_i8 v[74:77], v[62:65], v[178:181], v[74:77]
	v_mfma_i32_16x16x64_i8 v[66:69], v[58:61], v[182:185], v[66:69]
	v_mfma_i32_16x16x64_i8 v[66:69], v[62:65], v[186:189], v[66:69]
	v_mfma_i32_16x16x64_i8 v[50:53], v[58:61], v[190:193], v[50:53]
	v_mfma_i32_16x16x64_i8 v[50:53], v[62:65], v[200:203], v[50:53]
	v_mfma_i32_16x16x64_i8 v[2:5], v[58:61], v[204:207], v[6:9]
	v_mfma_i32_16x16x64_i8 v[34:37], v[62:65], v[208:211], v[2:5]
	v_mfma_i32_16x16x64_i8 v[2:5], v[146:149], v[174:177], v[10:13]
	v_mfma_i32_16x16x64_i8 v[62:65], v[150:153], v[178:181], v[2:5]
	v_mfma_i32_16x16x64_i8 v[2:5], v[154:157], v[174:177], v[14:17]
	v_mfma_i32_16x16x64_i8 v[58:61], v[158:161], v[178:181], v[2:5]
	v_mfma_i32_16x16x64_i8 v[2:5], v[146:149], v[182:185], v[46:49]
	v_mfma_i32_16x16x64_i8 v[46:49], v[150:153], v[186:189], v[2:5]
	v_mfma_i32_16x16x64_i8 v[2:5], v[154:157], v[182:185], v[42:45]
	v_mfma_i32_16x16x64_i8 v[42:45], v[158:161], v[186:189], v[2:5]
	v_mfma_i32_16x16x64_i8 v[2:5], v[146:149], v[190:193], v[30:33]
	v_mfma_i32_16x16x64_i8 v[30:33], v[150:153], v[200:203], v[2:5]
	v_mfma_i32_16x16x64_i8 v[2:5], v[154:157], v[190:193], v[26:29]
	v_mfma_i32_16x16x64_i8 v[26:29], v[158:161], v[200:203], v[2:5]
	v_mfma_i32_16x16x64_i8 v[2:5], v[146:149], v[204:207], v[22:25]
	v_mfma_i32_16x16x64_i8 v[22:25], v[150:153], v[208:211], v[2:5]
	v_mfma_i32_16x16x64_i8 v[2:5], v[154:157], v[204:207], v[18:21]
	v_mfma_i32_16x16x64_i8 v[18:21], v[158:161], v[208:211], v[2:5]
	s_barrier
	s_add_i32 s41, s41, 2
	s_add_u32 s0, s0, 0x100
	s_addc_u32 s1, s1, 0
	s_add_u32 s35, s35, 0x100
	s_addc_u32 s40, s40, 0
	s_cmp_gt_u32 s41, 29
	s_cbranch_scc0 .LBB0_300
	s_and_b64 vcc, exec, s[52:53]
	s_cbranch_vccz .LBB0_303
	s_barrier

.LBB0_576:
	s_ashr_i32 s23, s22, 31
	s_lshl_b64 s[26:27], s[22:23], 20
	s_add_u32 s26, s68, s26
	s_addc_u32 s27, s69, s27
	s_and_b64 s[28:29], s[40:41], exec
	s_cselect_b32 s19, s27, s31
	s_cselect_b32 s23, s26, s30
	s_ashr_i32 s25, s24, 31
	s_lshl_b64 s[28:29], s[24:25], 20
	s_add_u32 s28, s9, s28
	s_addc_u32 s29, s14, s29
	s_and_b64 s[42:43], s[40:41], exec
	s_cselect_b32 s25, s29, s35
	s_cselect_b32 s54, s28, s34
	s_add_u32 s30, s30, 0x80080
	s_addc_u32 s31, s31, 0
	s_add_u32 s55, s34, 0x100
	s_addc_u32 s56, s35, 0
	s_mov_b32 s57, -2
	.p2align 6
.LBB0_577:
	s_add_u32 s98, s30, 0xfff80000
	s_addc_u32 s99, s31, -1
	s_add_u32 s34, s30, 0xfff80080
	s_addc_u32 s35, s31, -1
	s_add_i32 s66, 0, 0x10000
	s_cmp_eq_u32 s57, 28
	s_cselect_b32 s43, s19, s35
	s_cselect_b32 s42, s23, s34
	v_add_u32_e32 v0, s66, v228
	s_cselect_b32 s35, s25, s56
	s_cselect_b32 s34, s54, s55
	s_add_i32 s73, 0, 0x14000
	ds_read_b128 v[132:135], v0
	ds_read_b128 v[136:139], v0 offset:1024
	ds_read_b128 v[140:143], v0 offset:2048
	ds_read_b128 v[144:147], v0 offset:3072
	v_add_u32_e32 v0, s73, v228
	ds_read_b128 v[148:151], v0
	ds_read_b128 v[152:155], v0 offset:1024
	ds_read_b128 v[156:159], v0 offset:2048
	ds_read_b128 v[160:163], v0 offset:3072
	s_mov_b32 m0, s50
	ds_read_b128 v[164:167], v230
	ds_read_b128 v[168:171], v230 offset:1024
	ds_read_b128 v[172:175], v230 offset:2048
	ds_read_b128 v[176:179], v230 offset:3072
	ds_read_b128 v[180:183], v230 offset:4096
	ds_read_b128 v[184:187], v230 offset:5120
	ds_read_b128 v[188:191], v230 offset:6144
	ds_read_b128 v[192:195], v230 offset:7168
	global_load_lds_dwordx4 v206, s[98:99]
	s_mov_b32 m0, s51
	s_nop 0
	global_load_lds_dwordx4 v202, s[98:99]
	s_add_i32 m0, s46, 0xc000
	s_nop 0
	global_load_lds_dwordx4 v208, s[30:31]
	s_add_i32 m0, s46, 0xe000
	s_nop 0
	global_load_lds_dwordx4 v210, s[30:31]
	s_waitcnt vmcnt(8)
	s_waitcnt lgkmcnt(0)
	s_barrier
	s_waitcnt lgkmcnt(0)
	v_mfma_f32_16x16x32_bf16 v[128:131], v[132:135], v[164:167], v[128:131]
	v_mfma_f32_16x16x32_bf16 v[128:131], v[136:139], v[168:171], v[128:131]
	v_mfma_f32_16x16x32_bf16 v[120:123], v[132:135], v[172:175], v[120:123]
	v_mfma_f32_16x16x32_bf16 v[120:123], v[136:139], v[176:179], v[120:123]
	v_mfma_f32_16x16x32_bf16 v[112:115], v[132:135], v[180:183], v[112:115]
	v_mfma_f32_16x16x32_bf16 v[112:115], v[136:139], v[184:187], v[112:115]
	v_mfma_f32_16x16x32_bf16 v[104:107], v[132:135], v[188:191], v[104:107]
	v_mfma_f32_16x16x32_bf16 v[104:107], v[136:139], v[192:195], v[104:107]
	v_mfma_f32_16x16x32_bf16 v[124:127], v[140:143], v[164:167], v[124:127]
	v_mfma_f32_16x16x32_bf16 v[124:127], v[144:147], v[168:171], v[124:127]
	v_mfma_f32_16x16x32_bf16 v[116:119], v[140:143], v[172:175], v[116:119]
	v_mfma_f32_16x16x32_bf16 v[116:119], v[144:147], v[176:179], v[116:119]
	v_mfma_f32_16x16x32_bf16 v[108:111], v[140:143], v[180:183], v[108:111]
	v_mfma_f32_16x16x32_bf16 v[108:111], v[144:147], v[184:187], v[108:111]
	v_mfma_f32_16x16x32_bf16 v[100:103], v[140:143], v[188:191], v[100:103]
	v_mfma_f32_16x16x32_bf16 v[100:103], v[144:147], v[192:195], v[100:103]
	v_mfma_f32_16x16x32_bf16 v[96:99], v[148:151], v[164:167], v[96:99]
	v_mfma_f32_16x16x32_bf16 v[96:99], v[152:155], v[168:171], v[96:99]
	v_mfma_f32_16x16x32_bf16 v[88:91], v[148:151], v[172:175], v[88:91]
	v_mfma_f32_16x16x32_bf16 v[88:91], v[152:155], v[176:179], v[88:91]
	v_mfma_f32_16x16x32_bf16 v[80:83], v[148:151], v[180:183], v[80:83]
	v_mfma_f32_16x16x32_bf16 v[80:83], v[152:155], v[184:187], v[80:83]
	v_mfma_f32_16x16x32_bf16 v[72:75], v[148:151], v[188:191], v[72:75]
	v_mfma_f32_16x16x32_bf16 v[72:75], v[152:155], v[192:195], v[72:75]
	v_mfma_f32_16x16x32_bf16 v[92:95], v[156:159], v[164:167], v[92:95]
	v_mfma_f32_16x16x32_bf16 v[92:95], v[160:163], v[168:171], v[92:95]
	v_mfma_f32_16x16x32_bf16 v[84:87], v[156:159], v[172:175], v[84:87]
	v_mfma_f32_16x16x32_bf16 v[84:87], v[160:163], v[176:179], v[84:87]
	v_mfma_f32_16x16x32_bf16 v[76:79], v[156:159], v[180:183], v[76:79]
	v_mfma_f32_16x16x32_bf16 v[76:79], v[160:163], v[184:187], v[76:79]
	v_mfma_f32_16x16x32_bf16 v[68:71], v[156:159], v[188:191], v[68:71]
	v_mfma_f32_16x16x32_bf16 v[68:71], v[160:163], v[192:195], v[68:71]
	s_barrier
	s_add_i32 s66, s66, s15
	s_mov_b32 m0, s66
	ds_read_b128 v[164:167], v230 offset:16384
	ds_read_b128 v[168:171], v230 offset:17408
	ds_read_b128 v[172:175], v230 offset:18432
	ds_read_b128 v[176:179], v230 offset:19456
	ds_read_b128 v[180:183], v230 offset:20480
	ds_read_b128 v[184:187], v230 offset:21504
	ds_read_b128 v[188:191], v230 offset:22528
	ds_read_b128 v[192:195], v230 offset:23552
	global_load_lds_dwordx4 v204, s[34:35]
	s_add_i32 m0, s66, 0x2000
	s_add_u32 s66, s34, 0x80000
	s_addc_u32 s67, s35, 0
	s_add_i32 s73, s73, s15
	global_load_lds_dwordx4 v200, s[34:35]
	s_mov_b32 m0, s73
	s_nop 0
	global_load_lds_dwordx4 v204, s[66:67]
	s_add_i32 m0, s73, 0x2000
	s_nop 0
	global_load_lds_dwordx4 v200, s[66:67]
	s_waitcnt vmcnt(6)
	s_waitcnt lgkmcnt(0)
	s_barrier
	s_waitcnt lgkmcnt(0)
	v_mfma_f32_16x16x32_bf16 v[64:67], v[132:135], v[164:167], v[64:67]
	v_mfma_f32_16x16x32_bf16 v[64:67], v[136:139], v[168:171], v[64:67]
	v_mfma_f32_16x16x32_bf16 v[56:59], v[132:135], v[172:175], v[56:59]
	v_mfma_f32_16x16x32_bf16 v[56:59], v[136:139], v[176:179], v[56:59]
	v_mfma_f32_16x16x32_bf16 v[48:51], v[132:135], v[180:183], v[48:51]
	v_mfma_f32_16x16x32_bf16 v[48:51], v[136:139], v[184:187], v[48:51]
	v_mfma_f32_16x16x32_bf16 v[40:43], v[132:135], v[188:191], v[40:43]
	v_mfma_f32_16x16x32_bf16 v[40:43], v[136:139], v[192:195], v[40:43]
	v_mfma_f32_16x16x32_bf16 v[60:63], v[140:143], v[164:167], v[60:63]
	v_mfma_f32_16x16x32_bf16 v[60:63], v[144:147], v[168:171], v[60:63]
	v_mfma_f32_16x16x32_bf16 v[52:55], v[140:143], v[172:175], v[52:55]
	v_mfma_f32_16x16x32_bf16 v[52:55], v[144:147], v[176:179], v[52:55]
	v_mfma_f32_16x16x32_bf16 v[44:47], v[140:143], v[180:183], v[44:47]
	v_mfma_f32_16x16x32_bf16 v[44:47], v[144:147], v[184:187], v[44:47]
	v_mfma_f32_16x16x32_bf16 v[36:39], v[140:143], v[188:191], v[36:39]
	v_mfma_f32_16x16x32_bf16 v[36:39], v[144:147], v[192:195], v[36:39]
	v_mfma_f32_16x16x32_bf16 v[32:35], v[148:151], v[164:167], v[32:35]
	v_mfma_f32_16x16x32_bf16 v[32:35], v[152:155], v[168:171], v[32:35]
	v_mfma_f32_16x16x32_bf16 v[28:31], v[156:159], v[164:167], v[28:31]
	v_mfma_f32_16x16x32_bf16 v[28:31], v[160:163], v[168:171], v[28:31]
	v_mfma_f32_16x16x32_bf16 v[24:27], v[148:151], v[172:175], v[24:27]
	v_mfma_f32_16x16x32_bf16 v[24:27], v[152:155], v[176:179], v[24:27]
	v_mfma_f32_16x16x32_bf16 v[20:23], v[156:159], v[172:175], v[20:23]
	v_mfma_f32_16x16x32_bf16 v[20:23], v[160:163], v[176:179], v[20:23]
	v_mfma_f32_16x16x32_bf16 v[16:19], v[148:151], v[180:183], v[16:19]
	v_mfma_f32_16x16x32_bf16 v[16:19], v[152:155], v[184:187], v[16:19]
	v_mfma_f32_16x16x32_bf16 v[12:15], v[156:159], v[180:183], v[12:15]
	v_mfma_f32_16x16x32_bf16 v[12:15], v[160:163], v[184:187], v[12:15]
	v_mfma_f32_16x16x32_bf16 v[8:11], v[148:151], v[188:191], v[8:11]
	v_mfma_f32_16x16x32_bf16 v[8:11], v[152:155], v[192:195], v[8:11]
	v_mfma_f32_16x16x32_bf16 v[2:5], v[156:159], v[188:191], v[4:7]
	v_mfma_f32_16x16x32_bf16 v[2:5], v[160:163], v[192:195], v[2:5]
	s_barrier
	s_nop 0
	s_add_i32 s66, 0, 0x18000
	v_add_u32_e32 v0, s66, v228
	s_add_i32 s67, 0, 0x1c000
	ds_read_b128 v[132:135], v0
	ds_read_b128 v[136:139], v0 offset:1024
	ds_read_b128 v[140:143], v0 offset:2048
	ds_read_b128 v[144:147], v0 offset:3072
	v_add_u32_e32 v0, s67, v228
	ds_read_b128 v[148:151], v0
	ds_read_b128 v[152:155], v0 offset:1024
	ds_read_b128 v[156:159], v0 offset:2048
	ds_read_b128 v[160:163], v0 offset:3072
	s_mov_b32 m0, s46
	ds_read_b128 v[164:167], v230 offset:32768
	ds_read_b128 v[168:171], v230 offset:33792
	ds_read_b128 v[172:175], v230 offset:34816
	ds_read_b128 v[176:179], v230 offset:35840
	ds_read_b128 v[180:183], v230 offset:36864
	ds_read_b128 v[184:187], v230 offset:37888
	ds_read_b128 v[188:191], v230 offset:38912
	ds_read_b128 v[192:195], v230 offset:39936
	global_load_lds_dwordx4 v206, s[42:43]
	s_mov_b32 m0, s47
	s_nop 0
	global_load_lds_dwordx4 v202, s[42:43]
	s_add_u32 s42, s42, 0x80000
	s_addc_u32 s43, s43, 0
	s_mov_b32 m0, s48
	s_nop 0
	global_load_lds_dwordx4 v206, s[42:43]
	s_mov_b32 m0, s49
	s_nop 0
	global_load_lds_dwordx4 v202, s[42:43]
	s_waitcnt vmcnt(8)
	s_waitcnt lgkmcnt(0)
	s_barrier
	s_waitcnt lgkmcnt(0)
	v_mfma_f32_16x16x32_bf16 v[128:131], v[132:135], v[164:167], v[128:131]
	v_mfma_f32_16x16x32_bf16 v[128:131], v[136:139], v[168:171], v[128:131]
	v_mfma_f32_16x16x32_bf16 v[120:123], v[132:135], v[172:175], v[120:123]
	v_mfma_f32_16x16x32_bf16 v[120:123], v[136:139], v[176:179], v[120:123]
	v_mfma_f32_16x16x32_bf16 v[112:115], v[132:135], v[180:183], v[112:115]
	v_mfma_f32_16x16x32_bf16 v[112:115], v[136:139], v[184:187], v[112:115]
	v_mfma_f32_16x16x32_bf16 v[104:107], v[132:135], v[188:191], v[104:107]
	v_mfma_f32_16x16x32_bf16 v[104:107], v[136:139], v[192:195], v[104:107]
	v_mfma_f32_16x16x32_bf16 v[124:127], v[140:143], v[164:167], v[124:127]
	v_mfma_f32_16x16x32_bf16 v[124:127], v[144:147], v[168:171], v[124:127]
	v_mfma_f32_16x16x32_bf16 v[116:119], v[140:143], v[172:175], v[116:119]
	v_mfma_f32_16x16x32_bf16 v[116:119], v[144:147], v[176:179], v[116:119]
	v_mfma_f32_16x16x32_bf16 v[108:111], v[140:143], v[180:183], v[108:111]
	v_mfma_f32_16x16x32_bf16 v[108:111], v[144:147], v[184:187], v[108:111]
	v_mfma_f32_16x16x32_bf16 v[100:103], v[140:143], v[188:191], v[100:103]
	v_mfma_f32_16x16x32_bf16 v[100:103], v[144:147], v[192:195], v[100:103]
	v_mfma_f32_16x16x32_bf16 v[96:99], v[148:151], v[164:167], v[96:99]
	v_mfma_f32_16x16x32_bf16 v[96:99], v[152:155], v[168:171], v[96:99]
	v_mfma_f32_16x16x32_bf16 v[88:91], v[148:151], v[172:175], v[88:91]
	v_mfma_f32_16x16x32_bf16 v[88:91], v[152:155], v[176:179], v[88:91]
	v_mfma_f32_16x16x32_bf16 v[80:83], v[148:151], v[180:183], v[80:83]
	v_mfma_f32_16x16x32_bf16 v[80:83], v[152:155], v[184:187], v[80:83]
	v_mfma_f32_16x16x32_bf16 v[72:75], v[148:151], v[188:191], v[72:75]
	v_mfma_f32_16x16x32_bf16 v[72:75], v[152:155], v[192:195], v[72:75]
	v_mfma_f32_16x16x32_bf16 v[92:95], v[156:159], v[164:167], v[92:95]
	v_mfma_f32_16x16x32_bf16 v[92:95], v[160:163], v[168:171], v[92:95]
	v_mfma_f32_16x16x32_bf16 v[84:87], v[156:159], v[172:175], v[84:87]
	v_mfma_f32_16x16x32_bf16 v[84:87], v[160:163], v[176:179], v[84:87]
	v_mfma_f32_16x16x32_bf16 v[76:79], v[156:159], v[180:183], v[76:79]
	v_mfma_f32_16x16x32_bf16 v[76:79], v[160:163], v[184:187], v[76:79]
	v_mfma_f32_16x16x32_bf16 v[68:71], v[156:159], v[188:191], v[68:71]
	v_mfma_f32_16x16x32_bf16 v[68:71], v[160:163], v[192:195], v[68:71]
	s_barrier
	s_nop 0
	s_add_i32 s42, s66, s15
	s_add_u32 s98, s34, 0x80
	s_addc_u32 s99, s35, 0
	s_mov_b32 m0, s42
	ds_read_b128 v[164:167], v230 offset:49152
	ds_read_b128 v[168:171], v230 offset:50176
	ds_read_b128 v[172:175], v230 offset:51200
	ds_read_b128 v[176:179], v230 offset:52224
	ds_read_b128 v[180:183], v230 offset:53248
	ds_read_b128 v[184:187], v230 offset:54272
	ds_read_b128 v[188:191], v230 offset:55296
	ds_read_b128 v[192:195], v230 offset:56320
	global_load_lds_dwordx4 v204, s[98:99]
	s_add_i32 m0, s42, 0x2000
	s_add_u32 s34, s34, 0x80080
	s_addc_u32 s35, s35, 0
	s_add_i32 s42, s67, s15
	global_load_lds_dwordx4 v200, s[98:99]
	s_mov_b32 m0, s42
	s_nop 0
	global_load_lds_dwordx4 v204, s[34:35]
	s_add_i32 m0, s42, 0x2000
	s_nop 0
	global_load_lds_dwordx4 v200, s[34:35]
	s_waitcnt vmcnt(6)
	s_waitcnt lgkmcnt(0)
	s_barrier
	s_waitcnt lgkmcnt(0)
	v_mfma_f32_16x16x32_bf16 v[64:67], v[132:135], v[164:167], v[64:67]
	v_mfma_f32_16x16x32_bf16 v[64:67], v[136:139], v[168:171], v[64:67]
	v_mfma_f32_16x16x32_bf16 v[56:59], v[132:135], v[172:175], v[56:59]
	v_mfma_f32_16x16x32_bf16 v[56:59], v[136:139], v[176:179], v[56:59]
	v_mfma_f32_16x16x32_bf16 v[48:51], v[132:135], v[180:183], v[48:51]
	v_mfma_f32_16x16x32_bf16 v[48:51], v[136:139], v[184:187], v[48:51]
	v_mfma_f32_16x16x32_bf16 v[40:43], v[132:135], v[188:191], v[40:43]
	v_mfma_f32_16x16x32_bf16 v[40:43], v[136:139], v[192:195], v[40:43]
	v_mfma_f32_16x16x32_bf16 v[60:63], v[140:143], v[164:167], v[60:63]
	v_mfma_f32_16x16x32_bf16 v[60:63], v[144:147], v[168:171], v[60:63]
	v_mfma_f32_16x16x32_bf16 v[52:55], v[140:143], v[172:175], v[52:55]
	v_mfma_f32_16x16x32_bf16 v[52:55], v[144:147], v[176:179], v[52:55]
	v_mfma_f32_16x16x32_bf16 v[44:47], v[140:143], v[180:183], v[44:47]
	v_mfma_f32_16x16x32_bf16 v[44:47], v[144:147], v[184:187], v[44:47]
	v_mfma_f32_16x16x32_bf16 v[36:39], v[140:143], v[188:191], v[36:39]
	v_mfma_f32_16x16x32_bf16 v[36:39], v[144:147], v[192:195], v[36:39]
	v_mfma_f32_16x16x32_bf16 v[32:35], v[148:151], v[164:167], v[32:35]
	v_mfma_f32_16x16x32_bf16 v[32:35], v[152:155], v[168:171], v[32:35]
	v_mfma_f32_16x16x32_bf16 v[28:31], v[156:159], v[164:167], v[28:31]
	v_mfma_f32_16x16x32_bf16 v[28:31], v[160:163], v[168:171], v[28:31]
	v_mfma_f32_16x16x32_bf16 v[24:27], v[148:151], v[172:175], v[24:27]
	v_mfma_f32_16x16x32_bf16 v[24:27], v[152:155], v[176:179], v[24:27]
	v_mfma_f32_16x16x32_bf16 v[20:23], v[156:159], v[172:175], v[20:23]
	v_mfma_f32_16x16x32_bf16 v[20:23], v[160:163], v[176:179], v[20:23]
	v_mfma_f32_16x16x32_bf16 v[16:19], v[148:151], v[180:183], v[16:19]
	v_mfma_f32_16x16x32_bf16 v[16:19], v[152:155], v[184:187], v[16:19]
	v_mfma_f32_16x16x32_bf16 v[12:15], v[156:159], v[180:183], v[12:15]
	v_mfma_f32_16x16x32_bf16 v[12:15], v[160:163], v[184:187], v[12:15]
	v_mfma_f32_16x16x32_bf16 v[6:9], v[148:151], v[188:191], v[8:11]
	v_mfma_f32_16x16x32_bf16 v[8:11], v[152:155], v[192:195], v[6:9]
	v_mfma_f32_16x16x32_bf16 v[2:5], v[156:159], v[188:191], v[2:5]
	v_mfma_f32_16x16x32_bf16 v[4:7], v[160:163], v[192:195], v[2:5]
	s_barrier
	s_add_i32 s57, s57, 2
	s_add_u32 s30, s30, 0x100
	s_addc_u32 s31, s31, 0
	s_add_u32 s55, s55, 0x100
	s_addc_u32 s56, s56, 0
	s_cmp_gt_u32 s57, 29
	s_cbranch_scc0 .LBB0_577
	s_and_b64 vcc, exec, s[20:21]
	s_cbranch_vccz .LBB0_580
	s_barrier

.LBB0_778:
	s_ashr_i32 s25, s24, 31
	s_lshl_b64 s[26:27], s[24:25], 20
	v_readlane_b32 s23, v253, 40
	s_add_u32 s26, s23, s26
	v_readlane_b32 s23, v253, 41
	s_addc_u32 s27, s23, s27
	s_and_b64 s[28:29], s[40:41], exec
	s_cselect_b32 s25, s27, s31
	s_cselect_b32 s53, s26, s30
	s_ashr_i32 s23, s22, 31
	s_lshl_b64 s[28:29], s[22:23], 20
	v_readlane_b32 s23, v253, 34
	s_add_u32 s28, s23, s28
	v_readlane_b32 s23, v253, 35
	s_addc_u32 s29, s23, s29
	s_and_b64 s[42:43], s[40:41], exec
	s_cselect_b32 s23, s29, s35
	s_cselect_b32 s54, s28, s34
	s_add_u32 s30, s30, 0x80080
	s_addc_u32 s31, s31, 0
	s_add_u32 s55, s34, 0x100
	v_mov_b64_e32 v[2:3], 0
	v_mov_b64_e32 v[4:5], 0
	v_mov_b64_e32 v[6:7], 0
	v_mov_b64_e32 v[8:9], 0
	v_mov_b64_e32 v[10:11], 0
	v_mov_b64_e32 v[12:13], 0
	v_mov_b64_e32 v[14:15], 0
	v_mov_b64_e32 v[16:17], 0
	v_mov_b64_e32 v[18:19], 0
	v_mov_b64_e32 v[20:21], 0
	v_mov_b64_e32 v[22:23], 0
	v_mov_b64_e32 v[24:25], 0
	v_mov_b64_e32 v[26:27], 0
	v_mov_b64_e32 v[28:29], 0
	v_mov_b64_e32 v[30:31], 0
	v_mov_b64_e32 v[32:33], 0
	v_mov_b64_e32 v[34:35], 0
	v_mov_b64_e32 v[36:37], 0
	v_mov_b64_e32 v[38:39], 0
	v_mov_b64_e32 v[40:41], 0
	v_mov_b64_e32 v[42:43], 0
	v_mov_b64_e32 v[44:45], 0
	v_mov_b64_e32 v[46:47], 0
	v_mov_b64_e32 v[48:49], 0
	v_mov_b64_e32 v[50:51], 0
	v_mov_b64_e32 v[52:53], 0
	v_mov_b64_e32 v[54:55], 0
	v_mov_b64_e32 v[56:57], 0
	v_mov_b64_e32 v[58:59], 0
	v_mov_b64_e32 v[60:61], 0
	v_mov_b64_e32 v[62:63], 0
	v_mov_b64_e32 v[64:65], 0
	v_mov_b64_e32 v[66:67], 0
	v_mov_b64_e32 v[68:69], 0
	v_mov_b64_e32 v[70:71], 0
	v_mov_b64_e32 v[72:73], 0
	v_mov_b64_e32 v[74:75], 0
	v_mov_b64_e32 v[76:77], 0
	v_mov_b64_e32 v[78:79], 0
	v_mov_b64_e32 v[80:81], 0
	v_mov_b64_e32 v[82:83], 0
	v_mov_b64_e32 v[84:85], 0
	v_mov_b64_e32 v[86:87], 0
	v_mov_b64_e32 v[88:89], 0
	v_mov_b64_e32 v[98:99], 0
	v_mov_b64_e32 v[100:101], 0
	v_mov_b64_e32 v[102:103], 0
	v_mov_b64_e32 v[104:105], 0
	v_mov_b64_e32 v[110:111], 0
	v_mov_b64_e32 v[112:113], 0
	v_mov_b64_e32 v[118:119], 0
	v_mov_b64_e32 v[120:121], 0
	v_mov_b64_e32 v[122:123], 0
	v_mov_b64_e32 v[124:125], 0
	v_mov_b64_e32 v[126:127], 0
	v_mov_b64_e32 v[128:129], 0
	v_mov_b64_e32 v[130:131], 0
	v_mov_b64_e32 v[132:133], 0
	v_mov_b64_e32 v[134:135], 0
	v_mov_b64_e32 v[136:137], 0
	v_mov_b64_e32 v[138:139], 0
	v_mov_b64_e32 v[140:141], 0
	v_mov_b64_e32 v[142:143], 0
	v_mov_b64_e32 v[144:145], 0
	s_addc_u32 s56, s35, 0
	s_mov_b32 s57, -2
	.p2align 6
.LBB0_779:
	s_add_u32 s98, s30, 0xfff80000
	s_addc_u32 s99, s31, -1
	s_add_u32 s34, s30, 0xfff80080
	s_addc_u32 s35, s31, -1
	s_add_i32 s66, 0, 0x10000
	s_cmp_eq_u32 s57, 28
	s_cselect_b32 s43, s25, s35
	s_cselect_b32 s42, s53, s34
	s_cselect_b32 s35, s23, s56
	s_cselect_b32 s34, s54, s55
	s_add_i32 s73, 0, 0x14000
	v_add_u32_e32 v114, s66, v157
	v_add_u32_e32 v156, s73, v157
	ds_read_b128 v[90:93], v114
	ds_read_b128 v[94:97], v114 offset:1024
	ds_read_b128 v[106:109], v114 offset:2048
	ds_read_b128 v[114:117], v114 offset:3072
	ds_read_b128 v[162:165], v156
	ds_read_b128 v[166:169], v156 offset:1024
	ds_read_b128 v[170:173], v156 offset:2048
	ds_read_b128 v[174:177], v156 offset:3072
	s_mov_b32 m0, s50
	ds_read_b128 v[178:181], v161
	ds_read_b128 v[182:185], v161 offset:1024
	ds_read_b128 v[186:189], v161 offset:2048
	ds_read_b128 v[190:193], v161 offset:3072
	ds_read_b128 v[200:203], v161 offset:4096
	ds_read_b128 v[204:207], v161 offset:5120
	ds_read_b128 v[208:211], v161 offset:6144
	ds_read_b128 v[212:215], v161 offset:7168
	global_load_lds_dwordx4 v150, s[98:99]
	s_mov_b32 m0, s51
	s_nop 0
	global_load_lds_dwordx4 v148, s[98:99]
	s_add_i32 m0, s14, 0xc000
	s_nop 0
	global_load_lds_dwordx4 v152, s[30:31]
	s_add_i32 m0, s14, 0xe000
	s_nop 0
	global_load_lds_dwordx4 v154, s[30:31]
	s_waitcnt vmcnt(8)
	s_waitcnt lgkmcnt(0)
	s_barrier
	s_waitcnt lgkmcnt(0)
	v_mfma_i32_16x16x64_i8 v[142:145], v[90:93], v[178:181], v[142:145]
	v_mfma_i32_16x16x64_i8 v[142:145], v[94:97], v[182:185], v[142:145]
	v_mfma_i32_16x16x64_i8 v[126:129], v[90:93], v[186:189], v[126:129]
	v_mfma_i32_16x16x64_i8 v[126:129], v[94:97], v[190:193], v[126:129]
	v_mfma_i32_16x16x64_i8 v[102:105], v[90:93], v[200:203], v[102:105]
	v_mfma_i32_16x16x64_i8 v[102:105], v[94:97], v[204:207], v[102:105]
	v_mfma_i32_16x16x64_i8 v[78:81], v[90:93], v[208:211], v[78:81]
	v_mfma_i32_16x16x64_i8 v[78:81], v[94:97], v[212:215], v[78:81]
	v_mfma_i32_16x16x64_i8 v[138:141], v[106:109], v[178:181], v[138:141]
	v_mfma_i32_16x16x64_i8 v[138:141], v[114:117], v[182:185], v[138:141]
	v_mfma_i32_16x16x64_i8 v[122:125], v[106:109], v[186:189], v[122:125]
	v_mfma_i32_16x16x64_i8 v[122:125], v[114:117], v[190:193], v[122:125]
	v_mfma_i32_16x16x64_i8 v[98:101], v[106:109], v[200:203], v[98:101]
	v_mfma_i32_16x16x64_i8 v[98:101], v[114:117], v[204:207], v[98:101]
	v_mfma_i32_16x16x64_i8 v[74:77], v[106:109], v[208:211], v[74:77]
	v_mfma_i32_16x16x64_i8 v[74:77], v[114:117], v[212:215], v[74:77]
	v_mfma_i32_16x16x64_i8 v[134:137], v[162:165], v[178:181], v[134:137]
	v_mfma_i32_16x16x64_i8 v[134:137], v[166:169], v[182:185], v[134:137]
	v_mfma_i32_16x16x64_i8 v[118:121], v[162:165], v[186:189], v[118:121]
	v_mfma_i32_16x16x64_i8 v[118:121], v[166:169], v[190:193], v[118:121]
	v_mfma_i32_16x16x64_i8 v[86:89], v[162:165], v[200:203], v[86:89]
	v_mfma_i32_16x16x64_i8 v[86:89], v[166:169], v[204:207], v[86:89]
	v_mfma_i32_16x16x64_i8 v[70:73], v[162:165], v[208:211], v[70:73]
	v_mfma_i32_16x16x64_i8 v[70:73], v[166:169], v[212:215], v[70:73]
	v_mfma_i32_16x16x64_i8 v[130:133], v[170:173], v[178:181], v[130:133]
	v_mfma_i32_16x16x64_i8 v[130:133], v[174:177], v[182:185], v[130:133]
	v_mfma_i32_16x16x64_i8 v[110:113], v[170:173], v[186:189], v[110:113]
	v_mfma_i32_16x16x64_i8 v[110:113], v[174:177], v[190:193], v[110:113]
	v_mfma_i32_16x16x64_i8 v[82:85], v[170:173], v[200:203], v[82:85]
	v_mfma_i32_16x16x64_i8 v[82:85], v[174:177], v[204:207], v[82:85]
	v_mfma_i32_16x16x64_i8 v[66:69], v[170:173], v[208:211], v[66:69]
	v_mfma_i32_16x16x64_i8 v[66:69], v[174:177], v[212:215], v[66:69]
	s_barrier
	s_add_i32 s66, s66, s9
	s_mov_b32 m0, s66
	ds_read_b128 v[178:181], v161 offset:16384
	ds_read_b128 v[182:185], v161 offset:17408
	ds_read_b128 v[186:189], v161 offset:18432
	ds_read_b128 v[190:193], v161 offset:19456
	ds_read_b128 v[200:203], v161 offset:20480
	ds_read_b128 v[204:207], v161 offset:21504
	ds_read_b128 v[208:211], v161 offset:22528
	ds_read_b128 v[212:215], v161 offset:23552
	global_load_lds_dwordx4 v0, s[34:35]
	s_add_i32 m0, s66, 0x2000
	s_add_u32 s66, s34, 0x80000
	s_addc_u32 s67, s35, 0
	s_add_i32 s73, s73, s9
	global_load_lds_dwordx4 v146, s[34:35]
	s_mov_b32 m0, s73
	s_nop 0
	global_load_lds_dwordx4 v0, s[66:67]
	s_add_i32 m0, s73, 0x2000
	s_nop 0
	global_load_lds_dwordx4 v146, s[66:67]
	s_waitcnt vmcnt(6)
	s_waitcnt lgkmcnt(0)
	s_barrier
	s_waitcnt lgkmcnt(0)
	v_mfma_i32_16x16x64_i8 v[62:65], v[90:93], v[178:181], v[62:65]
	v_mfma_i32_16x16x64_i8 v[62:65], v[94:97], v[182:185], v[62:65]
	v_mfma_i32_16x16x64_i8 v[46:49], v[90:93], v[186:189], v[46:49]
	v_mfma_i32_16x16x64_i8 v[46:49], v[94:97], v[190:193], v[46:49]
	v_mfma_i32_16x16x64_i8 v[30:33], v[90:93], v[200:203], v[30:33]
	v_mfma_i32_16x16x64_i8 v[30:33], v[94:97], v[204:207], v[30:33]
	v_mfma_i32_16x16x64_i8 v[14:17], v[90:93], v[208:211], v[14:17]
	v_mfma_i32_16x16x64_i8 v[14:17], v[94:97], v[212:215], v[14:17]
	v_mfma_i32_16x16x64_i8 v[58:61], v[106:109], v[178:181], v[58:61]
	v_mfma_i32_16x16x64_i8 v[58:61], v[114:117], v[182:185], v[58:61]
	v_mfma_i32_16x16x64_i8 v[42:45], v[106:109], v[186:189], v[42:45]
	v_mfma_i32_16x16x64_i8 v[42:45], v[114:117], v[190:193], v[42:45]
	v_mfma_i32_16x16x64_i8 v[26:29], v[106:109], v[200:203], v[26:29]
	v_mfma_i32_16x16x64_i8 v[26:29], v[114:117], v[204:207], v[26:29]
	v_mfma_i32_16x16x64_i8 v[10:13], v[106:109], v[208:211], v[10:13]
	v_mfma_i32_16x16x64_i8 v[10:13], v[114:117], v[212:215], v[10:13]
	v_mfma_i32_16x16x64_i8 v[54:57], v[162:165], v[178:181], v[54:57]
	v_mfma_i32_16x16x64_i8 v[54:57], v[166:169], v[182:185], v[54:57]
	v_mfma_i32_16x16x64_i8 v[38:41], v[162:165], v[186:189], v[38:41]
	v_mfma_i32_16x16x64_i8 v[38:41], v[166:169], v[190:193], v[38:41]
	v_mfma_i32_16x16x64_i8 v[22:25], v[162:165], v[200:203], v[22:25]
	v_mfma_i32_16x16x64_i8 v[22:25], v[166:169], v[204:207], v[22:25]
	v_mfma_i32_16x16x64_i8 v[6:9], v[162:165], v[208:211], v[6:9]
	v_mfma_i32_16x16x64_i8 v[6:9], v[166:169], v[212:215], v[6:9]
	v_mfma_i32_16x16x64_i8 v[50:53], v[170:173], v[178:181], v[50:53]
	v_mfma_i32_16x16x64_i8 v[50:53], v[174:177], v[182:185], v[50:53]
	v_mfma_i32_16x16x64_i8 v[34:37], v[170:173], v[186:189], v[34:37]
	v_mfma_i32_16x16x64_i8 v[34:37], v[174:177], v[190:193], v[34:37]
	v_mfma_i32_16x16x64_i8 v[18:21], v[170:173], v[200:203], v[18:21]
	v_mfma_i32_16x16x64_i8 v[18:21], v[174:177], v[204:207], v[18:21]
	v_mfma_i32_16x16x64_i8 v[2:5], v[170:173], v[208:211], v[2:5]
	v_mfma_i32_16x16x64_i8 v[2:5], v[174:177], v[212:215], v[2:5]
	s_barrier
	s_nop 0
	s_add_i32 s66, 0, 0x18000
	s_add_i32 s67, 0, 0x1c000
	v_add_u32_e32 v114, s66, v157
	v_add_u32_e32 v156, s67, v157
	ds_read_b128 v[90:93], v114
	ds_read_b128 v[94:97], v114 offset:1024
	ds_read_b128 v[106:109], v114 offset:2048
	ds_read_b128 v[114:117], v114 offset:3072
	ds_read_b128 v[162:165], v156
	ds_read_b128 v[166:169], v156 offset:1024
	ds_read_b128 v[170:173], v156 offset:2048
	ds_read_b128 v[174:177], v156 offset:3072
	s_mov_b32 m0, s14
	ds_read_b128 v[178:181], v161 offset:32768
	ds_read_b128 v[182:185], v161 offset:33792
	ds_read_b128 v[186:189], v161 offset:34816
	ds_read_b128 v[190:193], v161 offset:35840
	ds_read_b128 v[200:203], v161 offset:36864
	ds_read_b128 v[204:207], v161 offset:37888
	ds_read_b128 v[208:211], v161 offset:38912
	ds_read_b128 v[212:215], v161 offset:39936
	global_load_lds_dwordx4 v150, s[42:43]
	s_mov_b32 m0, s15
	s_nop 0
	global_load_lds_dwordx4 v148, s[42:43]
	s_add_u32 s42, s42, 0x80000
	s_addc_u32 s43, s43, 0
	s_mov_b32 m0, s46
	s_nop 0
	global_load_lds_dwordx4 v150, s[42:43]
	s_mov_b32 m0, s47
	s_nop 0
	global_load_lds_dwordx4 v148, s[42:43]
	s_waitcnt vmcnt(8)
	s_waitcnt lgkmcnt(0)
	s_barrier
	s_waitcnt lgkmcnt(0)
	v_mfma_i32_16x16x64_i8 v[142:145], v[90:93], v[178:181], v[142:145]
	v_mfma_i32_16x16x64_i8 v[142:145], v[94:97], v[182:185], v[142:145]
	v_mfma_i32_16x16x64_i8 v[126:129], v[90:93], v[186:189], v[126:129]
	v_mfma_i32_16x16x64_i8 v[126:129], v[94:97], v[190:193], v[126:129]
	v_mfma_i32_16x16x64_i8 v[102:105], v[90:93], v[200:203], v[102:105]
	v_mfma_i32_16x16x64_i8 v[102:105], v[94:97], v[204:207], v[102:105]
	v_mfma_i32_16x16x64_i8 v[78:81], v[90:93], v[208:211], v[78:81]
	v_mfma_i32_16x16x64_i8 v[78:81], v[94:97], v[212:215], v[78:81]
	v_mfma_i32_16x16x64_i8 v[138:141], v[106:109], v[178:181], v[138:141]
	v_mfma_i32_16x16x64_i8 v[138:141], v[114:117], v[182:185], v[138:141]
	v_mfma_i32_16x16x64_i8 v[122:125], v[106:109], v[186:189], v[122:125]
	v_mfma_i32_16x16x64_i8 v[122:125], v[114:117], v[190:193], v[122:125]
	v_mfma_i32_16x16x64_i8 v[98:101], v[106:109], v[200:203], v[98:101]
	v_mfma_i32_16x16x64_i8 v[98:101], v[114:117], v[204:207], v[98:101]
	v_mfma_i32_16x16x64_i8 v[74:77], v[106:109], v[208:211], v[74:77]
	v_mfma_i32_16x16x64_i8 v[74:77], v[114:117], v[212:215], v[74:77]
	v_mfma_i32_16x16x64_i8 v[134:137], v[162:165], v[178:181], v[134:137]
	v_mfma_i32_16x16x64_i8 v[134:137], v[166:169], v[182:185], v[134:137]
	v_mfma_i32_16x16x64_i8 v[118:121], v[162:165], v[186:189], v[118:121]
	v_mfma_i32_16x16x64_i8 v[118:121], v[166:169], v[190:193], v[118:121]
	v_mfma_i32_16x16x64_i8 v[86:89], v[162:165], v[200:203], v[86:89]
	v_mfma_i32_16x16x64_i8 v[86:89], v[166:169], v[204:207], v[86:89]
	v_mfma_i32_16x16x64_i8 v[70:73], v[162:165], v[208:211], v[70:73]
	v_mfma_i32_16x16x64_i8 v[70:73], v[166:169], v[212:215], v[70:73]
	v_mfma_i32_16x16x64_i8 v[130:133], v[170:173], v[178:181], v[130:133]
	v_mfma_i32_16x16x64_i8 v[130:133], v[174:177], v[182:185], v[130:133]
	v_mfma_i32_16x16x64_i8 v[110:113], v[170:173], v[186:189], v[110:113]
	v_mfma_i32_16x16x64_i8 v[110:113], v[174:177], v[190:193], v[110:113]
	v_mfma_i32_16x16x64_i8 v[82:85], v[170:173], v[200:203], v[82:85]
	v_mfma_i32_16x16x64_i8 v[82:85], v[174:177], v[204:207], v[82:85]
	v_mfma_i32_16x16x64_i8 v[66:69], v[170:173], v[208:211], v[66:69]
	v_mfma_i32_16x16x64_i8 v[66:69], v[174:177], v[212:215], v[66:69]
	s_barrier
	s_nop 0
	s_add_u32 s98, s34, 0x80
	s_addc_u32 s99, s35, 0
	s_add_i32 s42, s66, s9
	s_mov_b32 m0, s42
	ds_read_b128 v[178:181], v161 offset:49152
	ds_read_b128 v[182:185], v161 offset:50176
	ds_read_b128 v[186:189], v161 offset:51200
	ds_read_b128 v[190:193], v161 offset:52224
	ds_read_b128 v[200:203], v161 offset:53248
	ds_read_b128 v[204:207], v161 offset:54272
	ds_read_b128 v[208:211], v161 offset:55296
	ds_read_b128 v[212:215], v161 offset:56320
	global_load_lds_dwordx4 v0, s[98:99]
	s_add_i32 m0, s42, 0x2000
	s_add_u32 s34, s34, 0x80080
	s_addc_u32 s35, s35, 0
	s_add_i32 s42, s67, s9
	global_load_lds_dwordx4 v146, s[98:99]
	s_mov_b32 m0, s42
	s_nop 0
	global_load_lds_dwordx4 v0, s[34:35]
	s_add_i32 m0, s42, 0x2000
	s_nop 0
	global_load_lds_dwordx4 v146, s[34:35]
	s_waitcnt vmcnt(6)
	s_waitcnt lgkmcnt(0)
	s_barrier
	s_waitcnt lgkmcnt(0)
	v_mfma_i32_16x16x64_i8 v[62:65], v[90:93], v[178:181], v[62:65]
	v_mfma_i32_16x16x64_i8 v[62:65], v[94:97], v[182:185], v[62:65]
	v_mfma_i32_16x16x64_i8 v[46:49], v[90:93], v[186:189], v[46:49]
	v_mfma_i32_16x16x64_i8 v[46:49], v[94:97], v[190:193], v[46:49]
	v_mfma_i32_16x16x64_i8 v[30:33], v[90:93], v[200:203], v[30:33]
	v_mfma_i32_16x16x64_i8 v[30:33], v[94:97], v[204:207], v[30:33]
	v_mfma_i32_16x16x64_i8 v[14:17], v[90:93], v[208:211], v[14:17]
	v_mfma_i32_16x16x64_i8 v[14:17], v[94:97], v[212:215], v[14:17]
	v_mfma_i32_16x16x64_i8 v[58:61], v[106:109], v[178:181], v[58:61]
	v_mfma_i32_16x16x64_i8 v[58:61], v[114:117], v[182:185], v[58:61]
	v_mfma_i32_16x16x64_i8 v[42:45], v[106:109], v[186:189], v[42:45]
	v_mfma_i32_16x16x64_i8 v[42:45], v[114:117], v[190:193], v[42:45]
	v_mfma_i32_16x16x64_i8 v[26:29], v[106:109], v[200:203], v[26:29]
	v_mfma_i32_16x16x64_i8 v[26:29], v[114:117], v[204:207], v[26:29]
	v_mfma_i32_16x16x64_i8 v[10:13], v[106:109], v[208:211], v[10:13]
	v_mfma_i32_16x16x64_i8 v[10:13], v[114:117], v[212:215], v[10:13]
	v_mfma_i32_16x16x64_i8 v[54:57], v[162:165], v[178:181], v[54:57]
	v_mfma_i32_16x16x64_i8 v[54:57], v[166:169], v[182:185], v[54:57]
	v_mfma_i32_16x16x64_i8 v[38:41], v[162:165], v[186:189], v[38:41]
	v_mfma_i32_16x16x64_i8 v[38:41], v[166:169], v[190:193], v[38:41]
	v_mfma_i32_16x16x64_i8 v[22:25], v[162:165], v[200:203], v[22:25]
	v_mfma_i32_16x16x64_i8 v[22:25], v[166:169], v[204:207], v[22:25]
	v_mfma_i32_16x16x64_i8 v[6:9], v[162:165], v[208:211], v[6:9]
	v_mfma_i32_16x16x64_i8 v[6:9], v[166:169], v[212:215], v[6:9]
	v_mfma_i32_16x16x64_i8 v[50:53], v[170:173], v[178:181], v[50:53]
	v_mfma_i32_16x16x64_i8 v[50:53], v[174:177], v[182:185], v[50:53]
	v_mfma_i32_16x16x64_i8 v[34:37], v[170:173], v[186:189], v[34:37]
	v_mfma_i32_16x16x64_i8 v[34:37], v[174:177], v[190:193], v[34:37]
	v_mfma_i32_16x16x64_i8 v[18:21], v[170:173], v[200:203], v[18:21]
	v_mfma_i32_16x16x64_i8 v[18:21], v[174:177], v[204:207], v[18:21]
	v_mfma_i32_16x16x64_i8 v[2:5], v[170:173], v[208:211], v[2:5]
	v_mfma_i32_16x16x64_i8 v[2:5], v[174:177], v[212:215], v[2:5]
	s_barrier
	s_add_i32 s57, s57, 2
	s_add_u32 s30, s30, 0x100
	s_addc_u32 s31, s31, 0
	s_add_u32 s55, s55, 0x100
	s_addc_u32 s56, s56, 0
	s_cmp_gt_u32 s57, 29
	s_cbranch_scc0 .LBB0_779
	s_and_b64 vcc, exec, s[20:21]
	s_mov_b32 s54, 0x5c401000
	s_cbranch_vccz .LBB0_782
	s_barrier

.LBB0_800:
	s_ashr_i32 s25, s24, 31
	s_lshl_b64 s[26:27], s[24:25], 21
	s_add_u32 s26, s70, s26
	s_addc_u32 s27, s71, s27
	s_and_b64 s[28:29], s[38:39], exec
	s_cselect_b32 s25, s27, s31
	s_cselect_b32 s49, s26, s30
	s_ashr_i32 s23, s22, 31
	s_lshl_b64 s[28:29], s[22:23], 21
	v_readlane_b32 s23, v253, 52
	s_add_u32 s28, s23, s28
	v_readlane_b32 s23, v253, 53
	s_addc_u32 s29, s23, s29
	s_and_b64 s[40:41], s[38:39], exec
	s_cselect_b32 s23, s29, s35
	s_cselect_b32 s50, s28, s34
	s_add_u32 s30, s30, 0x100080
	s_addc_u32 s31, s31, 0
	s_add_u32 s51, s34, 0x100
	v_mov_b64_e32 v[2:3], 0
	v_mov_b64_e32 v[4:5], 0
	v_mov_b64_e32 v[6:7], 0
	v_mov_b64_e32 v[8:9], 0
	v_mov_b64_e32 v[10:11], 0
	v_mov_b64_e32 v[12:13], 0
	v_mov_b64_e32 v[14:15], 0
	v_mov_b64_e32 v[16:17], 0
	v_mov_b64_e32 v[18:19], 0
	v_mov_b64_e32 v[20:21], 0
	v_mov_b64_e32 v[22:23], 0
	v_mov_b64_e32 v[24:25], 0
	v_mov_b64_e32 v[26:27], 0
	v_mov_b64_e32 v[28:29], 0
	v_mov_b64_e32 v[30:31], 0
	v_mov_b64_e32 v[32:33], 0
	v_mov_b64_e32 v[34:35], 0
	v_mov_b64_e32 v[36:37], 0
	v_mov_b64_e32 v[38:39], 0
	v_mov_b64_e32 v[40:41], 0
	v_mov_b64_e32 v[42:43], 0
	v_mov_b64_e32 v[44:45], 0
	v_mov_b64_e32 v[46:47], 0
	v_mov_b64_e32 v[48:49], 0
	v_mov_b64_e32 v[50:51], 0
	v_mov_b64_e32 v[52:53], 0
	v_mov_b64_e32 v[54:55], 0
	v_mov_b64_e32 v[56:57], 0
	v_mov_b64_e32 v[58:59], 0
	v_mov_b64_e32 v[60:61], 0
	v_mov_b64_e32 v[62:63], 0
	v_mov_b64_e32 v[64:65], 0
	v_mov_b64_e32 v[66:67], 0
	v_mov_b64_e32 v[68:69], 0
	v_mov_b64_e32 v[70:71], 0
	v_mov_b64_e32 v[72:73], 0
	v_mov_b64_e32 v[74:75], 0
	v_mov_b64_e32 v[76:77], 0
	v_mov_b64_e32 v[78:79], 0
	v_mov_b64_e32 v[80:81], 0
	v_mov_b64_e32 v[82:83], 0
	v_mov_b64_e32 v[84:85], 0
	v_mov_b64_e32 v[86:87], 0
	v_mov_b64_e32 v[88:89], 0
	v_mov_b64_e32 v[90:91], 0
	v_mov_b64_e32 v[92:93], 0
	v_mov_b64_e32 v[94:95], 0
	v_mov_b64_e32 v[96:97], 0
	v_mov_b64_e32 v[98:99], 0
	v_mov_b64_e32 v[100:101], 0
	v_mov_b64_e32 v[102:103], 0
	v_mov_b64_e32 v[104:105], 0
	v_mov_b64_e32 v[106:107], 0
	v_mov_b64_e32 v[108:109], 0
	v_mov_b64_e32 v[110:111], 0
	v_mov_b64_e32 v[112:113], 0
	v_mov_b64_e32 v[114:115], 0
	v_mov_b64_e32 v[116:117], 0
	v_mov_b64_e32 v[118:119], 0
	v_mov_b64_e32 v[120:121], 0
	v_mov_b64_e32 v[122:123], 0
	v_mov_b64_e32 v[124:125], 0
	v_mov_b64_e32 v[126:127], 0
	v_mov_b64_e32 v[128:129], 0
	s_addc_u32 s52, s35, 0
	s_mov_b32 s53, -2
	.p2align 6
.LBB0_801:
	s_add_u32 s98, s30, 0xfff00000
	s_addc_u32 s99, s31, -1
	s_add_u32 s34, s30, 0xfff00080
	s_addc_u32 s35, s31, -1
	s_add_i32 s54, 0, 0x10000
	s_cmp_eq_u32 s53, 60
	s_cselect_b32 s41, s25, s35
	s_cselect_b32 s40, s49, s34
	s_cselect_b32 s35, s23, s52
	s_cselect_b32 s34, s50, s51
	s_add_i32 s56, 0, 0x14000
	v_add_u32_e32 v156, s54, v141
	v_add_u32_e32 v172, s56, v141
	ds_read_b128 v[144:147], v156
	ds_read_b128 v[148:151], v156 offset:1024
	ds_read_b128 v[152:155], v156 offset:2048
	ds_read_b128 v[156:159], v156 offset:3072
	ds_read_b128 v[160:163], v172
	ds_read_b128 v[164:167], v172 offset:1024
	ds_read_b128 v[168:171], v172 offset:2048
	ds_read_b128 v[172:175], v172 offset:3072
	s_mov_b32 m0, s42
	ds_read_b128 v[176:179], v143
	ds_read_b128 v[180:183], v143 offset:1024
	ds_read_b128 v[184:187], v143 offset:2048
	ds_read_b128 v[188:191], v143 offset:3072
	ds_read_b128 v[192:195], v143 offset:4096
	ds_read_b128 v[200:203], v143 offset:5120
	ds_read_b128 v[204:207], v143 offset:6144
	ds_read_b128 v[208:211], v143 offset:7168
	global_load_lds_dwordx4 v134, s[98:99]
	s_mov_b32 m0, s43
	s_nop 0
	global_load_lds_dwordx4 v132, s[98:99]
	s_add_i32 m0, s14, 0xc000
	s_nop 0
	global_load_lds_dwordx4 v136, s[30:31]
	s_add_i32 m0, s14, 0xe000
	s_nop 0
	global_load_lds_dwordx4 v138, s[30:31]
	s_waitcnt vmcnt(8)
	s_waitcnt lgkmcnt(0)
	s_barrier
	s_waitcnt lgkmcnt(0)
	v_mfma_f32_16x16x32_bf16 v[126:129], v[144:147], v[176:179], v[126:129]
	v_mfma_f32_16x16x32_bf16 v[126:129], v[148:151], v[180:183], v[126:129]
	v_mfma_f32_16x16x32_bf16 v[118:121], v[144:147], v[184:187], v[118:121]
	v_mfma_f32_16x16x32_bf16 v[118:121], v[148:151], v[188:191], v[118:121]
	v_mfma_f32_16x16x32_bf16 v[102:105], v[144:147], v[192:195], v[102:105]
	v_mfma_f32_16x16x32_bf16 v[102:105], v[148:151], v[200:203], v[102:105]
	v_mfma_f32_16x16x32_bf16 v[86:89], v[144:147], v[204:207], v[86:89]
	v_mfma_f32_16x16x32_bf16 v[86:89], v[148:151], v[208:211], v[86:89]
	v_mfma_f32_16x16x32_bf16 v[122:125], v[152:155], v[176:179], v[122:125]
	v_mfma_f32_16x16x32_bf16 v[122:125], v[156:159], v[180:183], v[122:125]
	v_mfma_f32_16x16x32_bf16 v[114:117], v[152:155], v[184:187], v[114:117]
	v_mfma_f32_16x16x32_bf16 v[114:117], v[156:159], v[188:191], v[114:117]
	v_mfma_f32_16x16x32_bf16 v[98:101], v[152:155], v[192:195], v[98:101]
	v_mfma_f32_16x16x32_bf16 v[98:101], v[156:159], v[200:203], v[98:101]
	v_mfma_f32_16x16x32_bf16 v[82:85], v[152:155], v[204:207], v[82:85]
	v_mfma_f32_16x16x32_bf16 v[82:85], v[156:159], v[208:211], v[82:85]
	v_mfma_f32_16x16x32_bf16 v[110:113], v[160:163], v[176:179], v[110:113]
	v_mfma_f32_16x16x32_bf16 v[110:113], v[164:167], v[180:183], v[110:113]
	v_mfma_f32_16x16x32_bf16 v[94:97], v[160:163], v[184:187], v[94:97]
	v_mfma_f32_16x16x32_bf16 v[94:97], v[164:167], v[188:191], v[94:97]
	v_mfma_f32_16x16x32_bf16 v[78:81], v[160:163], v[192:195], v[78:81]
	v_mfma_f32_16x16x32_bf16 v[78:81], v[164:167], v[200:203], v[78:81]
	v_mfma_f32_16x16x32_bf16 v[70:73], v[160:163], v[204:207], v[70:73]
	v_mfma_f32_16x16x32_bf16 v[70:73], v[164:167], v[208:211], v[70:73]
	v_mfma_f32_16x16x32_bf16 v[106:109], v[168:171], v[176:179], v[106:109]
	v_mfma_f32_16x16x32_bf16 v[106:109], v[172:175], v[180:183], v[106:109]
	v_mfma_f32_16x16x32_bf16 v[90:93], v[168:171], v[184:187], v[90:93]
	v_mfma_f32_16x16x32_bf16 v[90:93], v[172:175], v[188:191], v[90:93]
	v_mfma_f32_16x16x32_bf16 v[74:77], v[168:171], v[192:195], v[74:77]
	v_mfma_f32_16x16x32_bf16 v[74:77], v[172:175], v[200:203], v[74:77]
	v_mfma_f32_16x16x32_bf16 v[66:69], v[168:171], v[204:207], v[66:69]
	v_mfma_f32_16x16x32_bf16 v[66:69], v[172:175], v[208:211], v[66:69]
	s_barrier
	s_add_i32 s54, s54, s9
	s_mov_b32 m0, s54
	ds_read_b128 v[176:179], v143 offset:16384
	ds_read_b128 v[180:183], v143 offset:17408
	ds_read_b128 v[184:187], v143 offset:18432
	ds_read_b128 v[188:191], v143 offset:19456
	ds_read_b128 v[192:195], v143 offset:20480
	ds_read_b128 v[200:203], v143 offset:21504
	ds_read_b128 v[204:207], v143 offset:22528
	ds_read_b128 v[208:211], v143 offset:23552
	global_load_lds_dwordx4 v0, s[34:35]
	s_add_i32 m0, s54, 0x2000
	s_add_u32 s54, s34, 0x100000
	s_addc_u32 s55, s35, 0
	s_add_i32 s56, s56, s9
	global_load_lds_dwordx4 v130, s[34:35]
	s_mov_b32 m0, s56
	s_nop 0
	global_load_lds_dwordx4 v0, s[54:55]
	s_add_i32 m0, s56, 0x2000
	s_nop 0
	global_load_lds_dwordx4 v130, s[54:55]
	s_waitcnt vmcnt(6)
	s_waitcnt lgkmcnt(0)
	s_barrier
	s_waitcnt lgkmcnt(0)
	v_mfma_f32_16x16x32_bf16 v[62:65], v[144:147], v[176:179], v[62:65]
	v_mfma_f32_16x16x32_bf16 v[62:65], v[148:151], v[180:183], v[62:65]
	v_mfma_f32_16x16x32_bf16 v[54:57], v[144:147], v[184:187], v[54:57]
	v_mfma_f32_16x16x32_bf16 v[54:57], v[148:151], v[188:191], v[54:57]
	v_mfma_f32_16x16x32_bf16 v[38:41], v[144:147], v[192:195], v[38:41]
	v_mfma_f32_16x16x32_bf16 v[38:41], v[148:151], v[200:203], v[38:41]
	v_mfma_f32_16x16x32_bf16 v[22:25], v[144:147], v[204:207], v[22:25]
	v_mfma_f32_16x16x32_bf16 v[22:25], v[148:151], v[208:211], v[22:25]
	v_mfma_f32_16x16x32_bf16 v[58:61], v[152:155], v[176:179], v[58:61]
	v_mfma_f32_16x16x32_bf16 v[58:61], v[156:159], v[180:183], v[58:61]
	v_mfma_f32_16x16x32_bf16 v[50:53], v[152:155], v[184:187], v[50:53]
	v_mfma_f32_16x16x32_bf16 v[50:53], v[156:159], v[188:191], v[50:53]
	v_mfma_f32_16x16x32_bf16 v[34:37], v[152:155], v[192:195], v[34:37]
	v_mfma_f32_16x16x32_bf16 v[34:37], v[156:159], v[200:203], v[34:37]
	v_mfma_f32_16x16x32_bf16 v[18:21], v[152:155], v[204:207], v[18:21]
	v_mfma_f32_16x16x32_bf16 v[18:21], v[156:159], v[208:211], v[18:21]
	v_mfma_f32_16x16x32_bf16 v[46:49], v[160:163], v[176:179], v[46:49]
	v_mfma_f32_16x16x32_bf16 v[46:49], v[164:167], v[180:183], v[46:49]
	v_mfma_f32_16x16x32_bf16 v[30:33], v[160:163], v[184:187], v[30:33]
	v_mfma_f32_16x16x32_bf16 v[30:33], v[164:167], v[188:191], v[30:33]
	v_mfma_f32_16x16x32_bf16 v[14:17], v[160:163], v[192:195], v[14:17]
	v_mfma_f32_16x16x32_bf16 v[14:17], v[164:167], v[200:203], v[14:17]
	v_mfma_f32_16x16x32_bf16 v[6:9], v[160:163], v[204:207], v[6:9]
	v_mfma_f32_16x16x32_bf16 v[6:9], v[164:167], v[208:211], v[6:9]
	v_mfma_f32_16x16x32_bf16 v[42:45], v[168:171], v[176:179], v[42:45]
	v_mfma_f32_16x16x32_bf16 v[42:45], v[172:175], v[180:183], v[42:45]
	v_mfma_f32_16x16x32_bf16 v[26:29], v[168:171], v[184:187], v[26:29]
	v_mfma_f32_16x16x32_bf16 v[26:29], v[172:175], v[188:191], v[26:29]
	v_mfma_f32_16x16x32_bf16 v[10:13], v[168:171], v[192:195], v[10:13]
	v_mfma_f32_16x16x32_bf16 v[10:13], v[172:175], v[200:203], v[10:13]
	v_mfma_f32_16x16x32_bf16 v[2:5], v[168:171], v[204:207], v[2:5]
	v_mfma_f32_16x16x32_bf16 v[2:5], v[172:175], v[208:211], v[2:5]
	s_barrier
	s_nop 0
	s_add_i32 s54, 0, 0x18000
	s_add_i32 s55, 0, 0x1c000
	v_add_u32_e32 v156, s54, v141
	v_add_u32_e32 v172, s55, v141
	ds_read_b128 v[144:147], v156
	ds_read_b128 v[148:151], v156 offset:1024
	ds_read_b128 v[152:155], v156 offset:2048
	ds_read_b128 v[156:159], v156 offset:3072
	ds_read_b128 v[160:163], v172
	ds_read_b128 v[164:167], v172 offset:1024
	ds_read_b128 v[168:171], v172 offset:2048
	ds_read_b128 v[172:175], v172 offset:3072
	s_mov_b32 m0, s14
	ds_read_b128 v[176:179], v143 offset:32768
	ds_read_b128 v[180:183], v143 offset:33792
	ds_read_b128 v[184:187], v143 offset:34816
	ds_read_b128 v[188:191], v143 offset:35840
	ds_read_b128 v[192:195], v143 offset:36864
	ds_read_b128 v[200:203], v143 offset:37888
	ds_read_b128 v[204:207], v143 offset:38912
	ds_read_b128 v[208:211], v143 offset:39936
	global_load_lds_dwordx4 v134, s[40:41]
	s_mov_b32 m0, s15
	s_nop 0
	global_load_lds_dwordx4 v132, s[40:41]
	s_add_u32 s40, s40, 0x100000
	s_addc_u32 s41, s41, 0
	s_mov_b32 m0, s18
	s_nop 0
	global_load_lds_dwordx4 v134, s[40:41]
	s_mov_b32 m0, s19
	s_nop 0
	global_load_lds_dwordx4 v132, s[40:41]
	s_waitcnt vmcnt(8)
	s_waitcnt lgkmcnt(0)
	s_barrier
	s_waitcnt lgkmcnt(0)
	v_mfma_f32_16x16x32_bf16 v[126:129], v[144:147], v[176:179], v[126:129]
	v_mfma_f32_16x16x32_bf16 v[126:129], v[148:151], v[180:183], v[126:129]
	v_mfma_f32_16x16x32_bf16 v[118:121], v[144:147], v[184:187], v[118:121]
	v_mfma_f32_16x16x32_bf16 v[118:121], v[148:151], v[188:191], v[118:121]
	v_mfma_f32_16x16x32_bf16 v[102:105], v[144:147], v[192:195], v[102:105]
	v_mfma_f32_16x16x32_bf16 v[102:105], v[148:151], v[200:203], v[102:105]
	v_mfma_f32_16x16x32_bf16 v[86:89], v[144:147], v[204:207], v[86:89]
	v_mfma_f32_16x16x32_bf16 v[86:89], v[148:151], v[208:211], v[86:89]
	v_mfma_f32_16x16x32_bf16 v[122:125], v[152:155], v[176:179], v[122:125]
	v_mfma_f32_16x16x32_bf16 v[122:125], v[156:159], v[180:183], v[122:125]
	v_mfma_f32_16x16x32_bf16 v[114:117], v[152:155], v[184:187], v[114:117]
	v_mfma_f32_16x16x32_bf16 v[114:117], v[156:159], v[188:191], v[114:117]
	v_mfma_f32_16x16x32_bf16 v[98:101], v[152:155], v[192:195], v[98:101]
	v_mfma_f32_16x16x32_bf16 v[98:101], v[156:159], v[200:203], v[98:101]
	v_mfma_f32_16x16x32_bf16 v[82:85], v[152:155], v[204:207], v[82:85]
	v_mfma_f32_16x16x32_bf16 v[82:85], v[156:159], v[208:211], v[82:85]
	v_mfma_f32_16x16x32_bf16 v[110:113], v[160:163], v[176:179], v[110:113]
	v_mfma_f32_16x16x32_bf16 v[110:113], v[164:167], v[180:183], v[110:113]
	v_mfma_f32_16x16x32_bf16 v[94:97], v[160:163], v[184:187], v[94:97]
	v_mfma_f32_16x16x32_bf16 v[94:97], v[164:167], v[188:191], v[94:97]
	v_mfma_f32_16x16x32_bf16 v[78:81], v[160:163], v[192:195], v[78:81]
	v_mfma_f32_16x16x32_bf16 v[78:81], v[164:167], v[200:203], v[78:81]
	v_mfma_f32_16x16x32_bf16 v[70:73], v[160:163], v[204:207], v[70:73]
	v_mfma_f32_16x16x32_bf16 v[70:73], v[164:167], v[208:211], v[70:73]
	v_mfma_f32_16x16x32_bf16 v[106:109], v[168:171], v[176:179], v[106:109]
	v_mfma_f32_16x16x32_bf16 v[106:109], v[172:175], v[180:183], v[106:109]
	v_mfma_f32_16x16x32_bf16 v[90:93], v[168:171], v[184:187], v[90:93]
	v_mfma_f32_16x16x32_bf16 v[90:93], v[172:175], v[188:191], v[90:93]
	v_mfma_f32_16x16x32_bf16 v[74:77], v[168:171], v[192:195], v[74:77]
	v_mfma_f32_16x16x32_bf16 v[74:77], v[172:175], v[200:203], v[74:77]
	v_mfma_f32_16x16x32_bf16 v[66:69], v[168:171], v[204:207], v[66:69]
	v_mfma_f32_16x16x32_bf16 v[66:69], v[172:175], v[208:211], v[66:69]
	s_barrier
	s_nop 0
	s_add_u32 s98, s34, 0x80
	s_addc_u32 s99, s35, 0
	s_add_i32 s40, s54, s9
	s_mov_b32 m0, s40
	ds_read_b128 v[176:179], v143 offset:49152
	ds_read_b128 v[180:183], v143 offset:50176
	ds_read_b128 v[184:187], v143 offset:51200
	ds_read_b128 v[188:191], v143 offset:52224
	ds_read_b128 v[192:195], v143 offset:53248
	ds_read_b128 v[200:203], v143 offset:54272
	ds_read_b128 v[204:207], v143 offset:55296
	ds_read_b128 v[208:211], v143 offset:56320
	global_load_lds_dwordx4 v0, s[98:99]
	s_add_i32 m0, s40, 0x2000
	s_add_u32 s34, s34, 0x100080
	s_addc_u32 s35, s35, 0
	s_add_i32 s40, s55, s9
	global_load_lds_dwordx4 v130, s[98:99]
	s_mov_b32 m0, s40
	s_nop 0
	global_load_lds_dwordx4 v0, s[34:35]
	s_add_i32 m0, s40, 0x2000
	s_nop 0
	global_load_lds_dwordx4 v130, s[34:35]
	s_waitcnt vmcnt(6)
	s_waitcnt lgkmcnt(0)
	s_barrier
	s_waitcnt lgkmcnt(0)
	v_mfma_f32_16x16x32_bf16 v[62:65], v[144:147], v[176:179], v[62:65]
	v_mfma_f32_16x16x32_bf16 v[62:65], v[148:151], v[180:183], v[62:65]
	v_mfma_f32_16x16x32_bf16 v[54:57], v[144:147], v[184:187], v[54:57]
	v_mfma_f32_16x16x32_bf16 v[54:57], v[148:151], v[188:191], v[54:57]
	v_mfma_f32_16x16x32_bf16 v[38:41], v[144:147], v[192:195], v[38:41]
	v_mfma_f32_16x16x32_bf16 v[38:41], v[148:151], v[200:203], v[38:41]
	v_mfma_f32_16x16x32_bf16 v[22:25], v[144:147], v[204:207], v[22:25]
	v_mfma_f32_16x16x32_bf16 v[22:25], v[148:151], v[208:211], v[22:25]
	v_mfma_f32_16x16x32_bf16 v[58:61], v[152:155], v[176:179], v[58:61]
	v_mfma_f32_16x16x32_bf16 v[58:61], v[156:159], v[180:183], v[58:61]
	v_mfma_f32_16x16x32_bf16 v[50:53], v[152:155], v[184:187], v[50:53]
	v_mfma_f32_16x16x32_bf16 v[50:53], v[156:159], v[188:191], v[50:53]
	v_mfma_f32_16x16x32_bf16 v[34:37], v[152:155], v[192:195], v[34:37]
	v_mfma_f32_16x16x32_bf16 v[34:37], v[156:159], v[200:203], v[34:37]
	v_mfma_f32_16x16x32_bf16 v[18:21], v[152:155], v[204:207], v[18:21]
	v_mfma_f32_16x16x32_bf16 v[18:21], v[156:159], v[208:211], v[18:21]
	v_mfma_f32_16x16x32_bf16 v[46:49], v[160:163], v[176:179], v[46:49]
	v_mfma_f32_16x16x32_bf16 v[46:49], v[164:167], v[180:183], v[46:49]
	v_mfma_f32_16x16x32_bf16 v[30:33], v[160:163], v[184:187], v[30:33]
	v_mfma_f32_16x16x32_bf16 v[30:33], v[164:167], v[188:191], v[30:33]
	v_mfma_f32_16x16x32_bf16 v[14:17], v[160:163], v[192:195], v[14:17]
	v_mfma_f32_16x16x32_bf16 v[14:17], v[164:167], v[200:203], v[14:17]
	v_mfma_f32_16x16x32_bf16 v[6:9], v[160:163], v[204:207], v[6:9]
	v_mfma_f32_16x16x32_bf16 v[6:9], v[164:167], v[208:211], v[6:9]
	v_mfma_f32_16x16x32_bf16 v[42:45], v[168:171], v[176:179], v[42:45]
	v_mfma_f32_16x16x32_bf16 v[42:45], v[172:175], v[180:183], v[42:45]
	v_mfma_f32_16x16x32_bf16 v[26:29], v[168:171], v[184:187], v[26:29]
	v_mfma_f32_16x16x32_bf16 v[26:29], v[172:175], v[188:191], v[26:29]
	v_mfma_f32_16x16x32_bf16 v[10:13], v[168:171], v[192:195], v[10:13]
	v_mfma_f32_16x16x32_bf16 v[10:13], v[172:175], v[200:203], v[10:13]
	v_mfma_f32_16x16x32_bf16 v[2:5], v[168:171], v[204:207], v[2:5]
	v_mfma_f32_16x16x32_bf16 v[2:5], v[172:175], v[208:211], v[2:5]
	s_barrier
	s_add_i32 s53, s53, 2
	s_add_u32 s30, s30, 0x100
	s_addc_u32 s31, s31, 0
	s_add_u32 s51, s51, 0x100
	s_addc_u32 s52, s52, 0
	s_cmp_gt_u32 s53, 61
	s_cbranch_scc0 .LBB0_801
	s_and_b64 vcc, exec, s[20:21]
	s_cbranch_vccz .LBB0_804
	s_barrier
